# v030 + redundant canonicalizing v_max removed in branch-GEMM gate scaling (EpiBR mid/final)
# speedup vs baseline: 1.0052x; 1.0052x over previous
.LBB0_723:
	s_cmp_eq_u32 s4, s46
	s_cselect_b64 s[50:51], -1, 0
	s_add_u32 s18, s44, s46
	s_addc_u32 s19, s45, s47
	s_add_u32 s18, s18, 0x100
	s_addc_u32 s19, s19, 0
	s_and_b64 s[52:53], s[50:51], exec
	s_cselect_b32 s53, s79, s19
	s_cselect_b32 s52, s92, s18
	s_and_b64 vcc, s[38:39], s[50:51]
	s_and_b64 vcc, vcc, exec
	s_cselect_b32 s18, 0, s43
	s_cselect_b32 s19, 0x80000, s42
	s_add_i32 vcc_lo, 0, 0x10000
	s_add_u32 vcc_hi, s67, s46
	s_addc_u32 s25, s22, s47
	s_and_b64 s[50:51], s[50:51], exec
	v_add_u32_e32 v0, vcc_lo, v200
	s_cselect_b32 s51, s93, s25
	s_cselect_b32 s50, s21, vcc_hi
	s_add_i32 s25, 0, 0x14000
	ds_read_b128 v[132:135], v0
	ds_read_b128 v[136:139], v0 offset:1024
	ds_read_b128 v[140:143], v0 offset:2048
	ds_read_b128 v[144:147], v0 offset:3072
	v_add_u32_e32 v0, s25, v200
	ds_read_b128 v[148:151], v0
	ds_read_b128 v[152:155], v0 offset:1024
	ds_read_b128 v[156:159], v0 offset:2048
	ds_read_b128 v[160:163], v0 offset:3072
	v_lshl_add_u64 v[2:3], v[194:195], 0, s[46:47]
	s_add_i32 m0, s58, 0xc000
	ds_read_b128 v[164:167], v201
	ds_read_b128 v[168:171], v201 offset:1024
	ds_read_b128 v[172:175], v201 offset:2048
	ds_read_b128 v[202:205], v201 offset:3072
	ds_read_b128 v[206:209], v201 offset:4096
	ds_read_b128 v[210:213], v201 offset:5120
	ds_read_b128 v[214:217], v201 offset:6144
	ds_read_b128 v[218:221], v201 offset:7168
	global_load_lds_dwordx4 v[2:3], off
	v_lshl_add_u64 v[2:3], v[196:197], 0, s[46:47]
	s_add_i32 m0, s58, 0xe000
	s_nop 0
	global_load_lds_dwordx4 v[2:3], off
	s_waitcnt vmcnt(8)
	s_waitcnt lgkmcnt(0)
	s_barrier
	s_setprio 1
	s_waitcnt lgkmcnt(0)
	v_mfma_f32_16x16x32_bf16 v[128:131], v[132:135], v[164:167], v[128:131]
	v_mfma_f32_16x16x32_bf16 v[124:127], v[140:143], v[164:167], v[124:127]
	v_mfma_f32_16x16x32_bf16 v[112:115], v[132:135], v[172:175], v[112:115]
	v_mfma_f32_16x16x32_bf16 v[108:111], v[140:143], v[172:175], v[108:111]
	v_mfma_f32_16x16x32_bf16 v[96:99], v[132:135], v[206:209], v[96:99]
	v_mfma_f32_16x16x32_bf16 v[92:95], v[140:143], v[206:209], v[92:95]
	v_mfma_f32_16x16x32_bf16 v[80:83], v[132:135], v[214:217], v[80:83]
	v_mfma_f32_16x16x32_bf16 v[76:79], v[140:143], v[214:217], v[76:79]
	v_mfma_f32_16x16x32_bf16 v[128:131], v[136:139], v[168:171], v[128:131]
	v_mfma_f32_16x16x32_bf16 v[124:127], v[144:147], v[168:171], v[124:127]
	v_mfma_f32_16x16x32_bf16 v[112:115], v[136:139], v[202:205], v[112:115]
	v_mfma_f32_16x16x32_bf16 v[108:111], v[144:147], v[202:205], v[108:111]
	v_mfma_f32_16x16x32_bf16 v[96:99], v[136:139], v[210:213], v[96:99]
	v_mfma_f32_16x16x32_bf16 v[92:95], v[144:147], v[210:213], v[92:95]
	v_mfma_f32_16x16x32_bf16 v[80:83], v[136:139], v[218:221], v[80:83]
	v_mfma_f32_16x16x32_bf16 v[76:79], v[144:147], v[218:221], v[76:79]
	s_setprio 0
	s_setprio 1
	v_mfma_f32_16x16x32_bf16 v[120:123], v[148:151], v[164:167], v[120:123]
	v_mfma_f32_16x16x32_bf16 v[116:119], v[156:159], v[164:167], v[116:119]
	v_mfma_f32_16x16x32_bf16 v[104:107], v[148:151], v[172:175], v[104:107]
	v_mfma_f32_16x16x32_bf16 v[100:103], v[156:159], v[172:175], v[100:103]
	v_mfma_f32_16x16x32_bf16 v[88:91], v[148:151], v[206:209], v[88:91]
	v_mfma_f32_16x16x32_bf16 v[84:87], v[156:159], v[206:209], v[84:87]
	v_mfma_f32_16x16x32_bf16 v[72:75], v[148:151], v[214:217], v[72:75]
	v_mfma_f32_16x16x32_bf16 v[68:71], v[156:159], v[214:217], v[68:71]
	v_mfma_f32_16x16x32_bf16 v[120:123], v[152:155], v[168:171], v[120:123]
	v_mfma_f32_16x16x32_bf16 v[116:119], v[160:163], v[168:171], v[116:119]
	v_mfma_f32_16x16x32_bf16 v[104:107], v[152:155], v[202:205], v[104:107]
	v_mfma_f32_16x16x32_bf16 v[100:103], v[160:163], v[202:205], v[100:103]
	v_mfma_f32_16x16x32_bf16 v[88:91], v[152:155], v[210:213], v[88:91]
	v_mfma_f32_16x16x32_bf16 v[84:87], v[160:163], v[210:213], v[84:87]
	v_mfma_f32_16x16x32_bf16 v[72:75], v[152:155], v[218:221], v[72:75]
	v_mfma_f32_16x16x32_bf16 v[68:71], v[160:163], v[218:221], v[68:71]
	s_setprio 0
	s_barrier
	s_add_i32 vcc_lo, vcc_lo, s57
	v_lshl_add_u64 v[222:223], s[50:51], 0, v[184:185]
	s_mov_b32 m0, vcc_lo
	ds_read_b128 v[164:167], v201 offset:16384
	ds_read_b128 v[168:171], v201 offset:17408
	ds_read_b128 v[172:175], v201 offset:18432
	ds_read_b128 v[202:205], v201 offset:19456
	ds_read_b128 v[206:209], v201 offset:20480
	ds_read_b128 v[210:213], v201 offset:21504
	ds_read_b128 v[214:217], v201 offset:22528
	ds_read_b128 v[218:221], v201 offset:23552
	global_load_lds_dwordx4 v[222:223], off
	s_add_i32 m0, vcc_lo, 0x2000
	s_add_u32 vcc_lo, s50, 0x80000
	v_lshl_add_u64 v[224:225], s[50:51], 0, v[188:189]
	s_addc_u32 vcc_hi, s51, 0
	s_add_i32 s25, s25, s57
	global_load_lds_dwordx4 v[224:225], off
	v_lshl_add_u64 v[2:3], vcc, 0, v[184:185]
	s_mov_b32 m0, s25
	v_lshl_add_u64 v[226:227], s[52:53], 0, v[176:177]
	global_load_lds_dwordx4 v[2:3], off
	v_lshl_add_u64 v[2:3], vcc, 0, v[188:189]
	s_add_i32 m0, s25, 0x2000
	v_lshl_add_u64 v[230:231], s[52:53], 0, v[186:187]
	global_load_lds_dwordx4 v[2:3], off
	s_mov_b32 m0, s58
	s_nop 0
	global_load_lds_dwordx4 v[226:227], off
	s_mov_b32 m0, s59
	s_nop 0
	global_load_lds_dwordx4 v[230:231], off
	s_waitcnt vmcnt(8)
	s_waitcnt lgkmcnt(0)
	s_barrier
	s_setprio 1
	s_waitcnt lgkmcnt(0)
	v_mfma_f32_16x16x32_bf16 v[64:67], v[132:135], v[164:167], v[64:67]
	v_mfma_f32_16x16x32_bf16 v[60:63], v[140:143], v[164:167], v[60:63]
	v_mfma_f32_16x16x32_bf16 v[48:51], v[132:135], v[172:175], v[48:51]
	v_mfma_f32_16x16x32_bf16 v[44:47], v[140:143], v[172:175], v[44:47]
	v_mfma_f32_16x16x32_bf16 v[32:35], v[132:135], v[206:209], v[32:35]
	v_mfma_f32_16x16x32_bf16 v[28:31], v[140:143], v[206:209], v[28:31]
	v_mfma_f32_16x16x32_bf16 v[16:19], v[132:135], v[214:217], v[16:19]
	v_mfma_f32_16x16x32_bf16 v[12:15], v[140:143], v[214:217], v[12:15]
	v_mfma_f32_16x16x32_bf16 v[64:67], v[136:139], v[168:171], v[64:67]
	v_mfma_f32_16x16x32_bf16 v[60:63], v[144:147], v[168:171], v[60:63]
	v_mfma_f32_16x16x32_bf16 v[48:51], v[136:139], v[202:205], v[48:51]
	v_mfma_f32_16x16x32_bf16 v[44:47], v[144:147], v[202:205], v[44:47]
	v_mfma_f32_16x16x32_bf16 v[32:35], v[136:139], v[210:213], v[32:35]
	v_mfma_f32_16x16x32_bf16 v[28:31], v[144:147], v[210:213], v[28:31]
	v_mfma_f32_16x16x32_bf16 v[16:19], v[136:139], v[218:221], v[16:19]
	v_mfma_f32_16x16x32_bf16 v[12:15], v[144:147], v[218:221], v[12:15]
	s_setprio 0
	s_setprio 1
	v_mfma_f32_16x16x32_bf16 v[56:59], v[148:151], v[164:167], v[56:59]
	v_mfma_f32_16x16x32_bf16 v[52:55], v[156:159], v[164:167], v[52:55]
	v_mfma_f32_16x16x32_bf16 v[40:43], v[148:151], v[172:175], v[40:43]
	v_mfma_f32_16x16x32_bf16 v[36:39], v[156:159], v[172:175], v[36:39]
	v_mfma_f32_16x16x32_bf16 v[24:27], v[148:151], v[206:209], v[24:27]
	v_mfma_f32_16x16x32_bf16 v[20:23], v[156:159], v[206:209], v[20:23]
	v_mfma_f32_16x16x32_bf16 v[8:11], v[148:151], v[214:217], v[8:11]
	v_mfma_f32_16x16x32_bf16 v[2:5], v[156:159], v[214:217], v[4:7]
	v_mfma_f32_16x16x32_bf16 v[56:59], v[152:155], v[168:171], v[56:59]
	v_mfma_f32_16x16x32_bf16 v[52:55], v[160:163], v[168:171], v[52:55]
	v_mfma_f32_16x16x32_bf16 v[40:43], v[152:155], v[202:205], v[40:43]
	v_mfma_f32_16x16x32_bf16 v[36:39], v[160:163], v[202:205], v[36:39]
	v_mfma_f32_16x16x32_bf16 v[24:27], v[152:155], v[210:213], v[24:27]
	v_mfma_f32_16x16x32_bf16 v[20:23], v[160:163], v[210:213], v[20:23]
	v_mfma_f32_16x16x32_bf16 v[8:11], v[152:155], v[218:221], v[8:11]
	v_mfma_f32_16x16x32_bf16 v[2:5], v[160:163], v[218:221], v[2:5]
	s_setprio 0
	s_barrier
	s_add_i32 s25, 0, 0x18000
	v_add_u32_e32 v0, s25, v200
	s_add_i32 vcc_lo, 0, 0x1c000
	ds_read_b128 v[132:135], v0
	ds_read_b128 v[136:139], v0 offset:1024
	ds_read_b128 v[140:143], v0 offset:2048
	ds_read_b128 v[144:147], v0 offset:3072
	v_add_u32_e32 v0, vcc_lo, v200
	ds_read_b128 v[148:151], v0
	ds_read_b128 v[152:155], v0 offset:1024
	ds_read_b128 v[156:159], v0 offset:2048
	ds_read_b128 v[160:163], v0 offset:3072
	s_add_u32 s52, s52, s19
	s_addc_u32 s53, s53, s18
	s_mov_b32 m0, s82
	v_lshl_add_u64 v[6:7], s[52:53], 0, v[176:177]
	ds_read_b128 v[164:167], v201 offset:32768
	ds_read_b128 v[168:171], v201 offset:33792
	ds_read_b128 v[172:175], v201 offset:34816
	ds_read_b128 v[202:205], v201 offset:35840
	ds_read_b128 v[206:209], v201 offset:36864
	ds_read_b128 v[210:213], v201 offset:37888
	ds_read_b128 v[214:217], v201 offset:38912
	ds_read_b128 v[218:221], v201 offset:39936
	global_load_lds_dwordx4 v[6:7], off
	v_lshl_add_u64 v[6:7], s[52:53], 0, v[186:187]
	s_mov_b32 m0, s97
	s_nop 0
	global_load_lds_dwordx4 v[6:7], off
	s_waitcnt vmcnt(8)
	s_waitcnt lgkmcnt(0)
	s_barrier
	s_setprio 1
	s_waitcnt lgkmcnt(0)
	v_mfma_f32_16x16x32_bf16 v[128:131], v[132:135], v[164:167], v[128:131]
	v_mfma_f32_16x16x32_bf16 v[124:127], v[140:143], v[164:167], v[124:127]
	v_mfma_f32_16x16x32_bf16 v[112:115], v[132:135], v[172:175], v[112:115]
	v_mfma_f32_16x16x32_bf16 v[108:111], v[140:143], v[172:175], v[108:111]
	v_mfma_f32_16x16x32_bf16 v[96:99], v[132:135], v[206:209], v[96:99]
	v_mfma_f32_16x16x32_bf16 v[92:95], v[140:143], v[206:209], v[92:95]
	v_mfma_f32_16x16x32_bf16 v[80:83], v[132:135], v[214:217], v[80:83]
	v_mfma_f32_16x16x32_bf16 v[76:79], v[140:143], v[214:217], v[76:79]
	v_mfma_f32_16x16x32_bf16 v[128:131], v[136:139], v[168:171], v[128:131]
	v_mfma_f32_16x16x32_bf16 v[124:127], v[144:147], v[168:171], v[124:127]
	v_mfma_f32_16x16x32_bf16 v[112:115], v[136:139], v[202:205], v[112:115]
	v_mfma_f32_16x16x32_bf16 v[108:111], v[144:147], v[202:205], v[108:111]
	v_mfma_f32_16x16x32_bf16 v[96:99], v[136:139], v[210:213], v[96:99]
	v_mfma_f32_16x16x32_bf16 v[92:95], v[144:147], v[210:213], v[92:95]
	v_mfma_f32_16x16x32_bf16 v[80:83], v[136:139], v[218:221], v[80:83]
	v_mfma_f32_16x16x32_bf16 v[76:79], v[144:147], v[218:221], v[76:79]
	s_setprio 0
	s_setprio 1
	v_mfma_f32_16x16x32_bf16 v[120:123], v[148:151], v[164:167], v[120:123]
	v_mfma_f32_16x16x32_bf16 v[116:119], v[156:159], v[164:167], v[116:119]
	v_mfma_f32_16x16x32_bf16 v[104:107], v[148:151], v[172:175], v[104:107]
	v_mfma_f32_16x16x32_bf16 v[100:103], v[156:159], v[172:175], v[100:103]
	v_mfma_f32_16x16x32_bf16 v[88:91], v[148:151], v[206:209], v[88:91]
	v_mfma_f32_16x16x32_bf16 v[84:87], v[156:159], v[206:209], v[84:87]
	v_mfma_f32_16x16x32_bf16 v[72:75], v[148:151], v[214:217], v[72:75]
	v_mfma_f32_16x16x32_bf16 v[68:71], v[156:159], v[214:217], v[68:71]
	v_mfma_f32_16x16x32_bf16 v[120:123], v[152:155], v[168:171], v[120:123]
	v_mfma_f32_16x16x32_bf16 v[116:119], v[160:163], v[168:171], v[116:119]
	v_mfma_f32_16x16x32_bf16 v[104:107], v[152:155], v[202:205], v[104:107]
	v_mfma_f32_16x16x32_bf16 v[100:103], v[160:163], v[202:205], v[100:103]
	v_mfma_f32_16x16x32_bf16 v[88:91], v[152:155], v[210:213], v[88:91]
	v_mfma_f32_16x16x32_bf16 v[84:87], v[160:163], v[210:213], v[84:87]
	v_mfma_f32_16x16x32_bf16 v[72:75], v[152:155], v[218:221], v[72:75]
	v_mfma_f32_16x16x32_bf16 v[68:71], v[160:163], v[218:221], v[68:71]
	s_setprio 0
	s_barrier
	s_add_i32 s18, s25, s57
	v_lshl_add_u64 v[6:7], v[222:223], 0, s[90:91]
	s_mov_b32 m0, s18
	ds_read_b128 v[164:167], v201 offset:49152
	ds_read_b128 v[168:171], v201 offset:50176
	ds_read_b128 v[172:175], v201 offset:51200
	ds_read_b128 v[202:205], v201 offset:52224
	ds_read_b128 v[206:209], v201 offset:53248
	ds_read_b128 v[210:213], v201 offset:54272
	ds_read_b128 v[214:217], v201 offset:55296
	ds_read_b128 v[218:221], v201 offset:56320
	global_load_lds_dwordx4 v[6:7], off
	s_add_i32 m0, s18, 0x2000
	s_add_u32 s50, s50, 0x80080
	v_lshl_add_u64 v[6:7], v[224:225], 0, s[90:91]
	s_addc_u32 s51, s51, 0
	s_add_i32 s18, vcc_lo, s57
	global_load_lds_dwordx4 v[6:7], off
	v_lshl_add_u64 v[6:7], s[50:51], 0, v[184:185]
	s_mov_b32 m0, s18
	s_nop 0
	global_load_lds_dwordx4 v[6:7], off
	v_lshl_add_u64 v[6:7], s[50:51], 0, v[188:189]
	s_add_i32 m0, s18, 0x2000
	s_nop 0
	global_load_lds_dwordx4 v[6:7], off
	v_lshl_add_u64 v[6:7], v[226:227], 0, s[90:91]
	s_mov_b32 m0, s94
	s_nop 0
	global_load_lds_dwordx4 v[6:7], off
	v_lshl_add_u64 v[6:7], v[230:231], 0, s[90:91]
	s_mov_b32 m0, s54
	s_nop 0
	global_load_lds_dwordx4 v[6:7], off
	s_waitcnt vmcnt(8)
	s_waitcnt lgkmcnt(0)
	s_barrier
	s_setprio 1
	s_waitcnt lgkmcnt(0)
	v_mfma_f32_16x16x32_bf16 v[64:67], v[132:135], v[164:167], v[64:67]
	v_mfma_f32_16x16x32_bf16 v[60:63], v[140:143], v[164:167], v[60:63]
	v_mfma_f32_16x16x32_bf16 v[48:51], v[132:135], v[172:175], v[48:51]
	v_mfma_f32_16x16x32_bf16 v[44:47], v[140:143], v[172:175], v[44:47]
	v_mfma_f32_16x16x32_bf16 v[32:35], v[132:135], v[206:209], v[32:35]
	v_mfma_f32_16x16x32_bf16 v[28:31], v[140:143], v[206:209], v[28:31]
	v_mfma_f32_16x16x32_bf16 v[16:19], v[132:135], v[214:217], v[16:19]
	v_mfma_f32_16x16x32_bf16 v[12:15], v[140:143], v[214:217], v[12:15]
	v_mfma_f32_16x16x32_bf16 v[64:67], v[136:139], v[168:171], v[64:67]
	v_mfma_f32_16x16x32_bf16 v[60:63], v[144:147], v[168:171], v[60:63]
	v_mfma_f32_16x16x32_bf16 v[48:51], v[136:139], v[202:205], v[48:51]
	v_mfma_f32_16x16x32_bf16 v[44:47], v[144:147], v[202:205], v[44:47]
	v_mfma_f32_16x16x32_bf16 v[32:35], v[136:139], v[210:213], v[32:35]
	v_mfma_f32_16x16x32_bf16 v[28:31], v[144:147], v[210:213], v[28:31]
	v_mfma_f32_16x16x32_bf16 v[16:19], v[136:139], v[218:221], v[16:19]
	v_mfma_f32_16x16x32_bf16 v[12:15], v[144:147], v[218:221], v[12:15]
	s_setprio 0
	s_setprio 1
	v_mfma_f32_16x16x32_bf16 v[56:59], v[148:151], v[164:167], v[56:59]
	v_mfma_f32_16x16x32_bf16 v[52:55], v[156:159], v[164:167], v[52:55]
	v_mfma_f32_16x16x32_bf16 v[40:43], v[148:151], v[172:175], v[40:43]
	v_mfma_f32_16x16x32_bf16 v[36:39], v[156:159], v[172:175], v[36:39]
	v_mfma_f32_16x16x32_bf16 v[24:27], v[148:151], v[206:209], v[24:27]
	v_mfma_f32_16x16x32_bf16 v[20:23], v[156:159], v[206:209], v[20:23]
	v_mfma_f32_16x16x32_bf16 v[6:9], v[148:151], v[214:217], v[8:11]
	v_mfma_f32_16x16x32_bf16 v[2:5], v[156:159], v[214:217], v[2:5]
	v_mfma_f32_16x16x32_bf16 v[56:59], v[152:155], v[168:171], v[56:59]
	v_mfma_f32_16x16x32_bf16 v[52:55], v[160:163], v[168:171], v[52:55]
	v_mfma_f32_16x16x32_bf16 v[40:43], v[152:155], v[202:205], v[40:43]
	v_mfma_f32_16x16x32_bf16 v[36:39], v[160:163], v[202:205], v[36:39]
	v_mfma_f32_16x16x32_bf16 v[24:27], v[152:155], v[210:213], v[24:27]
	v_mfma_f32_16x16x32_bf16 v[20:23], v[160:163], v[210:213], v[20:23]
	v_mfma_f32_16x16x32_bf16 v[8:11], v[152:155], v[218:221], v[6:9]
	v_mfma_f32_16x16x32_bf16 v[4:7], v[160:163], v[218:221], v[2:5]
	s_setprio 0
	s_barrier
	s_and_b32 s18, s74, 6
	s_cmp_eq_u32 s18, 0
	s_cselect_b64 s[52:53], -1, 0
	s_cmp_ge_u32 s74, s1
	s_cselect_b64 s[50:51], -1, 0
	s_cmp_lt_u32 s74, s1
	s_cselect_b64 vcc, -1, 0
	s_and_b64 s[52:53], s[52:53], vcc
	s_andn2_b64 vcc, exec, s[52:53]
	s_cbranch_vccnz .LBB0_722
	s_lshr_b32 s18, s74, 3
	v_mov_b32_e32 v0, v199
	v_mov_b32_e32 v2, v198
	s_add_i32 s18, s18, s75
	v_add_u32_e32 v0, s89, v0
	s_lshl_b32 s18, s18, 12
	v_lshl_add_u32 v2, v2, 3, s78
	v_add_u32_e32 v132, s5, v0
	s_add_u32 s52, s28, s18
	v_ashrrev_i32_e32 v3, 31, v2
	s_addc_u32 s53, s29, 0
	v_ashrrev_i32_e32 v133, 31, v132
	v_lshl_add_u64 v[2:3], v[2:3], 1, s[52:53]
	v_lshlrev_b64 v[134:135], 14, v[132:133]
	v_lshl_add_u64 v[134:135], v[2:3], 0, v[134:135]
	global_load_dwordx4 v[202:205], v[134:135], off offset:-4096
	global_load_dwordx4 v[206:209], v[134:135], off
	global_load_dwordx4 v[210:213], v[134:135], off offset:-3840
	global_load_dwordx4 v[214:217], v[134:135], off offset:256
	v_add_u32_e32 v136, 16, v132
	v_add_u32_e32 v138, 32, v132
	v_add_u32_e32 v132, 48, v132
	v_ashrrev_i32_e32 v137, 31, v136
	v_ashrrev_i32_e32 v139, 31, v138
	v_ashrrev_i32_e32 v133, 31, v132
	v_lshlrev_b64 v[136:137], 14, v[136:137]
	v_lshlrev_b64 v[138:139], 14, v[138:139]
	v_lshlrev_b64 v[132:133], 14, v[132:133]
	v_lshl_add_u64 v[134:135], v[2:3], 0, v[136:137]
	v_lshl_add_u64 v[136:137], v[2:3], 0, v[138:139]
	v_lshl_add_u64 v[132:133], v[2:3], 0, v[132:133]
	global_load_dwordx4 v[218:221], v[134:135], off offset:-4096
	global_load_dwordx4 v[168:171], v[134:135], off offset:-3840
	global_load_dwordx4 v[172:175], v[134:135], off
	global_load_dwordx4 v[164:167], v[134:135], off offset:256
	global_load_dwordx4 v[160:163], v[136:137], off offset:-4096
	global_load_dwordx4 v[152:155], v[136:137], off offset:-3840
	global_load_dwordx4 v[156:159], v[136:137], off
	global_load_dwordx4 v[148:151], v[136:137], off offset:256
	global_load_dwordx4 v[144:147], v[132:133], off offset:-4096
	s_nop 0
	global_load_dwordx4 v[136:139], v[132:133], off offset:-3840
	global_load_dwordx4 v[140:143], v[132:133], off
	s_nop 0
	global_load_dwordx4 v[132:135], v[132:133], off offset:256
	s_waitcnt vmcnt(0)
	v_lshlrev_b32_e32 v222, 16, v202
	v_lshlrev_b32_e32 v223, 16, v203
	v_and_b32_e32 v203, 0xffff0000, v203
	v_lshlrev_b32_e32 v224, 16, v204
	v_lshlrev_b32_e32 v225, 16, v205
	v_lshlrev_b32_e32 v226, 16, v206
	v_and_b32_e32 v206, 0xffff0000, v206
	v_lshlrev_b32_e32 v227, 16, v207
	v_and_b32_e32 v207, 0xffff0000, v207
	v_lshlrev_b32_e32 v230, 16, v208
	v_and_b32_e32 v202, 0xffff0000, v202
	v_and_b32_e32 v204, 0xffff0000, v204
	v_and_b32_e32 v205, 0xffff0000, v205
	v_and_b32_e32 v231, 0xffff0000, v208
	v_lshlrev_b32_e32 v232, 16, v209
	v_and_b32_e32 v233, 0xffff0000, v209
	v_max_f32_e32 v208, v222, v222
	v_max_f32_e32 v222, v223, v223
	v_max_f32_e32 v238, v206, v206
	v_max_f32_e32 v239, v207, v207
	v_max_f32_e32 v209, v202, v202
	v_max_f32_e32 v234, v204, v204
	v_max_f32_e32 v235, v205, v205
	v_max_f32_e32 v202, 0x358637bd, v208
	v_max_f32_e32 v204, 0x358637bd, v222
	v_max_f32_e32 v205, 0x358637bd, v203
	v_max_f32_e32 v206, 0x358637bd, v224
	v_max_f32_e32 v208, 0x358637bd, v225
	v_max_f32_e32 v222, 0x358637bd, v226
	v_max_f32_e32 v223, 0x358637bd, v238
	v_max_f32_e32 v224, 0x358637bd, v227
	v_max_f32_e32 v225, 0x358637bd, v239
	v_max_f32_e32 v226, 0x358637bd, v230
	v_max_f32_e32 v227, v231, v231
	v_rcp_f32_e32 v222, v222
	v_rcp_f32_e32 v223, v223
	v_rcp_f32_e32 v224, v224
	v_rcp_f32_e32 v225, v225
	v_max_f32_e32 v227, 0x358637bd, v227
	v_max_f32_e32 v230, 0x358637bd, v232
	v_max_f32_e32 v231, 0x358637bd, v233
	v_rcp_f32_e32 v226, v226
	v_rcp_f32_e32 v227, v227
	v_rcp_f32_e32 v230, v230
	v_rcp_f32_e32 v231, v231
	v_max_f32_e32 v203, 0x358637bd, v209
	v_max_f32_e32 v207, 0x358637bd, v234
	v_max_f32_e32 v209, 0x358637bd, v235
	v_pk_mul_f32 v[202:203], v[202:203], v[222:223]
	v_pk_mul_f32 v[204:205], v[204:205], v[224:225]
	v_pk_mul_f32 v[128:129], v[128:129], v[202:203]
	v_pk_mul_f32 v[130:131], v[130:131], v[204:205]
	v_pk_mul_f32 v[202:203], v[206:207], v[226:227]
	v_pk_mul_f32 v[204:205], v[208:209], v[230:231]
	v_pk_mul_f32 v[124:125], v[124:125], v[202:203]
	v_pk_mul_f32 v[126:127], v[126:127], v[204:205]
	v_lshlrev_b32_e32 v202, 16, v210
	v_and_b32_e32 v203, 0xffff0000, v210
	v_lshlrev_b32_e32 v204, 16, v211
	v_and_b32_e32 v205, 0xffff0000, v211
	v_lshlrev_b32_e32 v210, 16, v214
	v_and_b32_e32 v211, 0xffff0000, v214
	v_lshlrev_b32_e32 v206, 16, v212
	v_and_b32_e32 v207, 0xffff0000, v212
	v_lshlrev_b32_e32 v208, 16, v213
	v_and_b32_e32 v209, 0xffff0000, v213
	v_lshlrev_b32_e32 v212, 16, v215
	v_and_b32_e32 v213, 0xffff0000, v215
	v_lshlrev_b32_e32 v214, 16, v216
	v_and_b32_e32 v215, 0xffff0000, v216
	v_lshlrev_b32_e32 v216, 16, v217
	v_and_b32_e32 v217, 0xffff0000, v217
	v_max_f32_e32 v210, 0x358637bd, v210
	v_max_f32_e32 v211, 0x358637bd, v211
	v_rcp_f32_e32 v210, v210
	v_rcp_f32_e32 v211, v211
	v_max_f32_e32 v212, 0x358637bd, v212
	v_max_f32_e32 v213, 0x358637bd, v213
	v_max_f32_e32 v214, 0x358637bd, v214
	v_max_f32_e32 v215, 0x358637bd, v215
	v_rcp_f32_e32 v212, v212
	v_rcp_f32_e32 v213, v213
	v_rcp_f32_e32 v214, v214
	v_rcp_f32_e32 v215, v215
	v_max_f32_e32 v216, 0x358637bd, v216
	v_max_f32_e32 v217, 0x358637bd, v217
	v_rcp_f32_e32 v216, v216
	v_rcp_f32_e32 v217, v217
	v_max_f32_e32 v202, 0x358637bd, v202
	v_max_f32_e32 v203, 0x358637bd, v203
	v_max_f32_e32 v204, 0x358637bd, v204
	v_max_f32_e32 v205, 0x358637bd, v205
	v_max_f32_e32 v206, 0x358637bd, v206
	v_max_f32_e32 v207, 0x358637bd, v207
	v_pk_mul_f32 v[202:203], v[202:203], v[210:211]
	v_lshlrev_b32_e32 v210, 16, v172
	v_and_b32_e32 v211, 0xffff0000, v172
	v_max_f32_e32 v208, 0x358637bd, v208
	v_max_f32_e32 v209, 0x358637bd, v209
	v_pk_mul_f32 v[204:205], v[204:205], v[212:213]
	v_pk_mul_f32 v[120:121], v[120:121], v[202:203]
	v_pk_mul_f32 v[202:203], v[206:207], v[214:215]
	v_lshlrev_b32_e32 v212, 16, v173
	v_and_b32_e32 v213, 0xffff0000, v173
	v_lshlrev_b32_e32 v214, 16, v174
	v_and_b32_e32 v215, 0xffff0000, v174
	v_pk_mul_f32 v[122:123], v[122:123], v[204:205]
	v_pk_mul_f32 v[204:205], v[208:209], v[216:217]
	v_lshlrev_b32_e32 v216, 16, v175
	v_and_b32_e32 v217, 0xffff0000, v175
	v_max_f32_e32 v172, 0x358637bd, v210
	v_max_f32_e32 v173, 0x358637bd, v211
	v_rcp_f32_e32 v172, v172
	v_rcp_f32_e32 v173, v173
	v_max_f32_e32 v174, 0x358637bd, v212
	v_max_f32_e32 v175, 0x358637bd, v213
	v_max_f32_e32 v210, 0x358637bd, v214
	v_max_f32_e32 v211, 0x358637bd, v215
	v_pk_mul_f32 v[116:117], v[116:117], v[202:203]
	v_lshlrev_b32_e32 v202, 16, v218
	v_and_b32_e32 v203, 0xffff0000, v218
	v_rcp_f32_e32 v174, v174
	v_rcp_f32_e32 v175, v175
	v_rcp_f32_e32 v210, v210
	v_rcp_f32_e32 v211, v211
	v_max_f32_e32 v212, 0x358637bd, v216
	v_max_f32_e32 v213, 0x358637bd, v217
	v_pk_mul_f32 v[118:119], v[118:119], v[204:205]
	v_lshlrev_b32_e32 v204, 16, v219
	v_and_b32_e32 v205, 0xffff0000, v219
	v_lshlrev_b32_e32 v206, 16, v220
	v_and_b32_e32 v207, 0xffff0000, v220
	v_rcp_f32_e32 v212, v212
	v_rcp_f32_e32 v213, v213
	v_lshlrev_b32_e32 v208, 16, v221
	v_and_b32_e32 v209, 0xffff0000, v221
	v_max_f32_e32 v202, 0x358637bd, v202
	v_max_f32_e32 v203, 0x358637bd, v203
	v_max_f32_e32 v204, 0x358637bd, v204
	v_max_f32_e32 v205, 0x358637bd, v205
	v_max_f32_e32 v206, 0x358637bd, v206
	v_max_f32_e32 v207, 0x358637bd, v207
	v_pk_mul_f32 v[172:173], v[202:203], v[172:173]
	v_max_f32_e32 v208, 0x358637bd, v208
	v_max_f32_e32 v209, 0x358637bd, v209
	v_pk_mul_f32 v[174:175], v[204:205], v[174:175]
	v_pk_mul_f32 v[112:113], v[112:113], v[172:173]
	v_pk_mul_f32 v[172:173], v[206:207], v[210:211]
	v_pk_mul_f32 v[114:115], v[114:115], v[174:175]
	v_pk_mul_f32 v[174:175], v[208:209], v[212:213]
	v_pk_mul_f32 v[108:109], v[108:109], v[172:173]
	v_lshlrev_b32_e32 v172, 16, v168
	v_and_b32_e32 v173, 0xffff0000, v168
	v_lshlrev_b32_e32 v202, 16, v170
	v_and_b32_e32 v203, 0xffff0000, v170
	v_pk_mul_f32 v[110:111], v[110:111], v[174:175]
	v_lshlrev_b32_e32 v174, 16, v169
	v_and_b32_e32 v175, 0xffff0000, v169
	v_lshlrev_b32_e32 v204, 16, v171
	v_and_b32_e32 v205, 0xffff0000, v171
	v_max_f32_e32 v168, v172, v172
	v_max_f32_e32 v169, v173, v173
	v_max_f32_e32 v172, v202, v202
	v_max_f32_e32 v173, v203, v203
	v_lshlrev_b32_e32 v202, 16, v164
	v_and_b32_e32 v203, 0xffff0000, v164
	v_max_f32_e32 v170, v174, v174
	v_max_f32_e32 v171, v175, v175
	v_max_f32_e32 v174, v204, v204
	v_max_f32_e32 v175, v205, v205
	v_lshlrev_b32_e32 v204, 16, v165
	v_and_b32_e32 v205, 0xffff0000, v165
	v_lshlrev_b32_e32 v206, 16, v166
	v_and_b32_e32 v207, 0xffff0000, v166
	v_lshlrev_b32_e32 v208, 16, v167
	v_and_b32_e32 v209, 0xffff0000, v167
	v_max_f32_e32 v164, 0x358637bd, v202
	v_max_f32_e32 v165, 0x358637bd, v203
	v_rcp_f32_e32 v164, v164
	v_rcp_f32_e32 v165, v165
	v_max_f32_e32 v166, 0x358637bd, v204
	v_max_f32_e32 v167, 0x358637bd, v205
	v_max_f32_e32 v202, 0x358637bd, v206
	v_max_f32_e32 v203, 0x358637bd, v207
	v_rcp_f32_e32 v166, v166
	v_rcp_f32_e32 v167, v167
	v_rcp_f32_e32 v202, v202
	v_rcp_f32_e32 v203, v203
	v_max_f32_e32 v204, 0x358637bd, v208
	v_max_f32_e32 v205, 0x358637bd, v209
	v_rcp_f32_e32 v204, v204
	v_rcp_f32_e32 v205, v205
	v_max_f32_e32 v168, 0x358637bd, v168
	v_max_f32_e32 v169, 0x358637bd, v169
	v_max_f32_e32 v170, 0x358637bd, v170
	v_max_f32_e32 v171, 0x358637bd, v171
	v_max_f32_e32 v172, 0x358637bd, v172
	v_max_f32_e32 v173, 0x358637bd, v173
	v_pk_mul_f32 v[164:165], v[168:169], v[164:165]
	v_max_f32_e32 v174, 0x358637bd, v174
	v_max_f32_e32 v175, 0x358637bd, v175
	v_pk_mul_f32 v[166:167], v[170:171], v[166:167]
	v_pk_mul_f32 v[104:105], v[104:105], v[164:165]
	v_pk_mul_f32 v[164:165], v[172:173], v[202:203]
	v_pk_mul_f32 v[106:107], v[106:107], v[166:167]
	v_pk_mul_f32 v[166:167], v[174:175], v[204:205]
	v_pk_mul_f32 v[100:101], v[100:101], v[164:165]
	v_lshlrev_b32_e32 v164, 16, v160
	v_and_b32_e32 v165, 0xffff0000, v160
	v_lshlrev_b32_e32 v168, 16, v162
	v_and_b32_e32 v169, 0xffff0000, v162
	v_pk_mul_f32 v[102:103], v[102:103], v[166:167]
	v_lshlrev_b32_e32 v166, 16, v161
	v_and_b32_e32 v167, 0xffff0000, v161
	v_lshlrev_b32_e32 v170, 16, v163
	v_and_b32_e32 v171, 0xffff0000, v163
	v_max_f32_e32 v160, v164, v164
	v_max_f32_e32 v161, v165, v165
	v_max_f32_e32 v164, v168, v168
	v_max_f32_e32 v165, v169, v169
	v_lshlrev_b32_e32 v168, 16, v156
	v_and_b32_e32 v169, 0xffff0000, v156
	v_max_f32_e32 v162, v166, v166
	v_max_f32_e32 v163, v167, v167
	v_max_f32_e32 v166, v170, v170
	v_max_f32_e32 v167, v171, v171
	v_lshlrev_b32_e32 v170, 16, v157
	v_and_b32_e32 v171, 0xffff0000, v157
	v_lshlrev_b32_e32 v172, 16, v158
	v_and_b32_e32 v173, 0xffff0000, v158
	v_lshlrev_b32_e32 v174, 16, v159
	v_and_b32_e32 v175, 0xffff0000, v159
	v_max_f32_e32 v156, 0x358637bd, v168
	v_max_f32_e32 v157, 0x358637bd, v169
	v_rcp_f32_e32 v156, v156
	v_rcp_f32_e32 v157, v157
	v_max_f32_e32 v158, 0x358637bd, v170
	v_max_f32_e32 v159, 0x358637bd, v171
	v_max_f32_e32 v168, 0x358637bd, v172
	v_max_f32_e32 v169, 0x358637bd, v173
	v_rcp_f32_e32 v158, v158
	v_rcp_f32_e32 v159, v159
	v_rcp_f32_e32 v168, v168
	v_rcp_f32_e32 v169, v169
	v_max_f32_e32 v170, 0x358637bd, v174
	v_max_f32_e32 v171, 0x358637bd, v175
	v_rcp_f32_e32 v170, v170
	v_rcp_f32_e32 v171, v171
	v_max_f32_e32 v160, 0x358637bd, v160
	v_max_f32_e32 v161, 0x358637bd, v161
	v_max_f32_e32 v162, 0x358637bd, v162
	v_max_f32_e32 v163, 0x358637bd, v163
	v_max_f32_e32 v164, 0x358637bd, v164
	v_max_f32_e32 v165, 0x358637bd, v165
	v_pk_mul_f32 v[156:157], v[160:161], v[156:157]
	v_max_f32_e32 v166, 0x358637bd, v166
	v_max_f32_e32 v167, 0x358637bd, v167
	v_pk_mul_f32 v[158:159], v[162:163], v[158:159]
	v_pk_mul_f32 v[96:97], v[96:97], v[156:157]
	v_pk_mul_f32 v[156:157], v[164:165], v[168:169]
	v_pk_mul_f32 v[98:99], v[98:99], v[158:159]
	v_pk_mul_f32 v[158:159], v[166:167], v[170:171]
	v_pk_mul_f32 v[92:93], v[92:93], v[156:157]
	v_lshlrev_b32_e32 v156, 16, v152
	v_and_b32_e32 v157, 0xffff0000, v152
	v_lshlrev_b32_e32 v160, 16, v154
	v_and_b32_e32 v161, 0xffff0000, v154
	v_pk_mul_f32 v[94:95], v[94:95], v[158:159]
	v_lshlrev_b32_e32 v158, 16, v153
	v_and_b32_e32 v159, 0xffff0000, v153
	v_lshlrev_b32_e32 v162, 16, v155
	v_and_b32_e32 v163, 0xffff0000, v155
	v_max_f32_e32 v152, v156, v156
	v_max_f32_e32 v153, v157, v157
	v_max_f32_e32 v156, v160, v160
	v_max_f32_e32 v157, v161, v161
	v_lshlrev_b32_e32 v160, 16, v148
	v_and_b32_e32 v161, 0xffff0000, v148
	v_max_f32_e32 v154, v158, v158
	v_max_f32_e32 v155, v159, v159
	v_max_f32_e32 v158, v162, v162
	v_max_f32_e32 v159, v163, v163
	v_lshlrev_b32_e32 v162, 16, v149
	v_and_b32_e32 v163, 0xffff0000, v149
	v_lshlrev_b32_e32 v164, 16, v150
	v_and_b32_e32 v165, 0xffff0000, v150
	v_lshlrev_b32_e32 v166, 16, v151
	v_and_b32_e32 v167, 0xffff0000, v151
	v_max_f32_e32 v148, 0x358637bd, v160
	v_max_f32_e32 v149, 0x358637bd, v161
	v_rcp_f32_e32 v148, v148
	v_rcp_f32_e32 v149, v149
	v_max_f32_e32 v150, 0x358637bd, v162
	v_max_f32_e32 v151, 0x358637bd, v163
	v_max_f32_e32 v160, 0x358637bd, v164
	v_max_f32_e32 v161, 0x358637bd, v165
	v_rcp_f32_e32 v150, v150
	v_rcp_f32_e32 v151, v151
	v_rcp_f32_e32 v160, v160
	v_rcp_f32_e32 v161, v161
	v_max_f32_e32 v162, 0x358637bd, v166
	v_max_f32_e32 v163, 0x358637bd, v167
	v_rcp_f32_e32 v162, v162
	v_rcp_f32_e32 v163, v163
	v_max_f32_e32 v152, 0x358637bd, v152
	v_max_f32_e32 v153, 0x358637bd, v153
	v_max_f32_e32 v154, 0x358637bd, v154
	v_max_f32_e32 v155, 0x358637bd, v155
	v_max_f32_e32 v156, 0x358637bd, v156
	v_max_f32_e32 v157, 0x358637bd, v157
	v_pk_mul_f32 v[148:149], v[152:153], v[148:149]
	v_max_f32_e32 v158, 0x358637bd, v158
	v_max_f32_e32 v159, 0x358637bd, v159
	v_pk_mul_f32 v[150:151], v[154:155], v[150:151]
	v_pk_mul_f32 v[88:89], v[88:89], v[148:149]
	v_pk_mul_f32 v[148:149], v[156:157], v[160:161]
	v_pk_mul_f32 v[90:91], v[90:91], v[150:151]
	v_pk_mul_f32 v[150:151], v[158:159], v[162:163]
	v_pk_mul_f32 v[84:85], v[84:85], v[148:149]
	v_lshlrev_b32_e32 v148, 16, v144
	v_and_b32_e32 v149, 0xffff0000, v144
	v_lshlrev_b32_e32 v152, 16, v146
	v_and_b32_e32 v153, 0xffff0000, v146
	v_pk_mul_f32 v[86:87], v[86:87], v[150:151]
	v_lshlrev_b32_e32 v150, 16, v145
	v_and_b32_e32 v151, 0xffff0000, v145
	v_lshlrev_b32_e32 v154, 16, v147
	v_and_b32_e32 v155, 0xffff0000, v147
	v_max_f32_e32 v144, v148, v148
	v_max_f32_e32 v145, v149, v149
	v_max_f32_e32 v148, v152, v152
	v_max_f32_e32 v149, v153, v153
	v_lshlrev_b32_e32 v152, 16, v140
	v_and_b32_e32 v153, 0xffff0000, v140
	v_max_f32_e32 v146, v150, v150
	v_max_f32_e32 v147, v151, v151
	v_max_f32_e32 v150, v154, v154
	v_max_f32_e32 v151, v155, v155
	v_lshlrev_b32_e32 v154, 16, v141
	v_and_b32_e32 v155, 0xffff0000, v141
	v_lshlrev_b32_e32 v156, 16, v142
	v_and_b32_e32 v157, 0xffff0000, v142
	v_lshlrev_b32_e32 v158, 16, v143
	v_and_b32_e32 v159, 0xffff0000, v143
	v_max_f32_e32 v140, 0x358637bd, v152
	v_max_f32_e32 v141, 0x358637bd, v153
	v_rcp_f32_e32 v140, v140
	v_rcp_f32_e32 v141, v141
	v_max_f32_e32 v142, 0x358637bd, v154
	v_max_f32_e32 v143, 0x358637bd, v155
	v_max_f32_e32 v152, 0x358637bd, v156
	v_max_f32_e32 v153, 0x358637bd, v157
	v_rcp_f32_e32 v142, v142
	v_rcp_f32_e32 v143, v143
	v_rcp_f32_e32 v152, v152
	v_rcp_f32_e32 v153, v153
	v_max_f32_e32 v154, 0x358637bd, v158
	v_max_f32_e32 v155, 0x358637bd, v159
	v_rcp_f32_e32 v154, v154
	v_rcp_f32_e32 v155, v155
	v_max_f32_e32 v144, 0x358637bd, v144
	v_max_f32_e32 v145, 0x358637bd, v145
	v_max_f32_e32 v146, 0x358637bd, v146
	v_max_f32_e32 v147, 0x358637bd, v147
	v_max_f32_e32 v148, 0x358637bd, v148
	v_max_f32_e32 v149, 0x358637bd, v149
	v_pk_mul_f32 v[140:141], v[144:145], v[140:141]
	v_max_f32_e32 v150, 0x358637bd, v150
	v_max_f32_e32 v151, 0x358637bd, v151
	v_pk_mul_f32 v[142:143], v[146:147], v[142:143]
	v_pk_mul_f32 v[80:81], v[80:81], v[140:141]
	v_pk_mul_f32 v[140:141], v[148:149], v[152:153]
	v_lshlrev_b32_e32 v144, 16, v138
	v_and_b32_e32 v145, 0xffff0000, v138
	v_add_u32_e32 v138, s95, v0
	v_pk_mul_f32 v[82:83], v[82:83], v[142:143]
	v_pk_mul_f32 v[142:143], v[150:151], v[154:155]
	v_pk_mul_f32 v[76:77], v[76:77], v[140:141]
	v_lshlrev_b32_e32 v140, 16, v136
	v_and_b32_e32 v141, 0xffff0000, v136
	v_lshlrev_b32_e32 v146, 16, v139
	v_and_b32_e32 v147, 0xffff0000, v139
	v_ashrrev_i32_e32 v139, 31, v138
	v_pk_mul_f32 v[78:79], v[78:79], v[142:143]
	v_lshlrev_b32_e32 v142, 16, v137
	v_and_b32_e32 v143, 0xffff0000, v137
	v_max_f32_e32 v136, v140, v140
	v_max_f32_e32 v137, v141, v141
	v_lshlrev_b64 v[140:141], 14, v[138:139]
	v_lshl_add_u64 v[140:141], v[2:3], 0, v[140:141]
	global_load_dwordx4 v[172:175], v[140:141], off offset:-4096
	global_load_dwordx4 v[202:205], v[140:141], off
	global_load_dwordx4 v[206:209], v[140:141], off offset:-3840
	global_load_dwordx4 v[210:213], v[140:141], off offset:256
	v_max_f32_e32 v142, 0x358637bd, v142
	v_max_f32_e32 v143, 0x358637bd, v143
	v_max_f32_e32 v144, 0x358637bd, v144
	v_max_f32_e32 v145, 0x358637bd, v145
	v_max_f32_e32 v146, 0x358637bd, v146
	v_max_f32_e32 v147, 0x358637bd, v147
	v_lshlrev_b32_e32 v0, 16, v132
	v_and_b32_e32 v139, 0xffff0000, v132
	v_max_f32_e32 v0, 0x358637bd, v0
	v_rcp_f32_e32 v132, v0
	v_lshlrev_b32_e32 v148, 16, v133
	v_max_f32_e32 v0, 0x358637bd, v139
	v_and_b32_e32 v149, 0xffff0000, v133
	v_rcp_f32_e32 v133, v0
	v_max_f32_e32 v0, 0x358637bd, v148
	v_lshlrev_b32_e32 v150, 16, v134
	v_and_b32_e32 v151, 0xffff0000, v134
	v_rcp_f32_e32 v134, v0
	v_max_f32_e32 v0, 0x358637bd, v149
	v_lshlrev_b32_e32 v152, 16, v135
	v_and_b32_e32 v153, 0xffff0000, v135
	v_rcp_f32_e32 v135, v0
	v_max_f32_e32 v0, 0x358637bd, v150
	v_rcp_f32_e32 v148, v0
	v_max_f32_e32 v0, 0x358637bd, v151
	v_rcp_f32_e32 v149, v0
	v_max_f32_e32 v136, 0x358637bd, v136
	v_max_f32_e32 v137, 0x358637bd, v137
	v_pk_mul_f32 v[132:133], v[136:137], v[132:133]
	v_pk_mul_f32 v[72:73], v[72:73], v[132:133]
	v_pk_mul_f32 v[132:133], v[144:145], v[148:149]
	v_max_f32_e32 v0, 0x358637bd, v152
	v_pk_mul_f32 v[68:69], v[68:69], v[132:133]
	v_add_u32_e32 v132, 16, v138
	v_ashrrev_i32_e32 v133, 31, v132
	v_lshlrev_b64 v[132:133], 14, v[132:133]
	v_lshl_add_u64 v[132:133], v[2:3], 0, v[132:133]
	global_load_dwordx4 v[214:217], v[132:133], off offset:-4096
	global_load_dwordx4 v[168:171], v[132:133], off offset:-3840
	global_load_dwordx4 v[218:221], v[132:133], off
	global_load_dwordx4 v[164:167], v[132:133], off offset:256
	v_rcp_f32_e32 v150, v0
	v_max_f32_e32 v0, 0x358637bd, v153
	v_rcp_f32_e32 v151, v0
	v_add_u32_e32 v132, 32, v138
	v_ashrrev_i32_e32 v133, 31, v132
	v_lshlrev_b64 v[132:133], 14, v[132:133]
	v_pk_mul_f32 v[134:135], v[142:143], v[134:135]
	v_lshl_add_u64 v[132:133], v[2:3], 0, v[132:133]
	v_pk_mul_f32 v[74:75], v[74:75], v[134:135]
	v_pk_mul_f32 v[134:135], v[146:147], v[150:151]
	global_load_dwordx4 v[160:163], v[132:133], off offset:-4096
	global_load_dwordx4 v[152:155], v[132:133], off offset:-3840
	global_load_dwordx4 v[156:159], v[132:133], off
	global_load_dwordx4 v[148:151], v[132:133], off offset:256
	v_add_u32_e32 v132, 48, v138
	v_ashrrev_i32_e32 v133, 31, v132
	v_lshlrev_b64 v[132:133], 14, v[132:133]
	v_lshl_add_u64 v[2:3], v[2:3], 0, v[132:133]
	v_pk_mul_f32 v[70:71], v[70:71], v[134:135]
	global_load_dwordx4 v[144:147], v[2:3], off offset:-4096
	global_load_dwordx4 v[136:139], v[2:3], off offset:-3840
	global_load_dwordx4 v[140:143], v[2:3], off
	global_load_dwordx4 v[132:135], v[2:3], off offset:256
	s_waitcnt vmcnt(15)
	v_lshlrev_b32_e32 v0, 16, v172
	v_and_b32_e32 v3, 0xffff0000, v172
	v_lshlrev_b32_e32 v172, 16, v173
	v_max_f32_e32 v2, 0x358637bd, v0
	v_and_b32_e32 v173, 0xffff0000, v173
	v_max_f32_e32 v3, 0x358637bd, v3
	v_lshlrev_b32_e32 v222, 16, v174
	v_max_f32_e32 v172, 0x358637bd, v172
	v_and_b32_e32 v223, 0xffff0000, v174
	v_max_f32_e32 v173, 0x358637bd, v173
	v_lshlrev_b32_e32 v224, 16, v175
	v_max_f32_e32 v174, 0x358637bd, v222
	v_and_b32_e32 v225, 0xffff0000, v175
	v_max_f32_e32 v175, 0x358637bd, v223
	v_max_f32_e32 v222, 0x358637bd, v224
	v_max_f32_e32 v223, 0x358637bd, v225
	s_waitcnt vmcnt(14)
	v_lshlrev_b32_e32 v0, 16, v202
	v_and_b32_e32 v224, 0xffff0000, v202
	v_max_f32_e32 v0, 0x358637bd, v0
	v_rcp_f32_e32 v202, v0
	v_lshlrev_b32_e32 v225, 16, v203
	v_max_f32_e32 v0, 0x358637bd, v224
	v_and_b32_e32 v226, 0xffff0000, v203
	v_rcp_f32_e32 v203, v0
	v_max_f32_e32 v0, 0x358637bd, v225
	v_lshlrev_b32_e32 v227, 16, v204
	v_and_b32_e32 v230, 0xffff0000, v204
	v_rcp_f32_e32 v204, v0
	v_max_f32_e32 v0, 0x358637bd, v226
	v_lshlrev_b32_e32 v231, 16, v205
	v_and_b32_e32 v232, 0xffff0000, v205
	v_rcp_f32_e32 v205, v0
	v_max_f32_e32 v0, 0x358637bd, v227
	v_rcp_f32_e32 v224, v0
	v_max_f32_e32 v0, 0x358637bd, v230
	v_rcp_f32_e32 v225, v0
	v_max_f32_e32 v0, 0x358637bd, v231
	v_rcp_f32_e32 v226, v0
	v_max_f32_e32 v0, 0x358637bd, v232
	v_rcp_f32_e32 v227, v0
	v_pk_mul_f32 v[2:3], v[2:3], v[202:203]
	v_pk_mul_f32 v[172:173], v[172:173], v[204:205]
	v_pk_mul_f32 v[64:65], v[64:65], v[2:3]
	v_pk_mul_f32 v[2:3], v[174:175], v[224:225]
	s_waitcnt vmcnt(13)
	v_lshlrev_b32_e32 v0, 16, v206
	v_pk_mul_f32 v[66:67], v[66:67], v[172:173]
	v_pk_mul_f32 v[172:173], v[222:223], v[226:227]
	v_pk_mul_f32 v[60:61], v[60:61], v[2:3]
	v_and_b32_e32 v3, 0xffff0000, v206
	v_pk_mul_f32 v[62:63], v[62:63], v[172:173]
	v_lshlrev_b32_e32 v172, 16, v207
	v_max_f32_e32 v2, 0x358637bd, v0
	v_and_b32_e32 v173, 0xffff0000, v207
	v_max_f32_e32 v3, 0x358637bd, v3
	v_lshlrev_b32_e32 v174, 16, v208
	v_max_f32_e32 v172, 0x358637bd, v172
	v_and_b32_e32 v175, 0xffff0000, v208
	v_max_f32_e32 v173, 0x358637bd, v173
	v_lshlrev_b32_e32 v202, 16, v209
	v_max_f32_e32 v174, 0x358637bd, v174
	v_and_b32_e32 v203, 0xffff0000, v209
	v_max_f32_e32 v175, 0x358637bd, v175
	v_max_f32_e32 v202, 0x358637bd, v202
	v_max_f32_e32 v203, 0x358637bd, v203
	s_waitcnt vmcnt(12)
	v_lshlrev_b32_e32 v0, 16, v210
	v_and_b32_e32 v205, 0xffff0000, v210
	v_max_f32_e32 v0, 0x358637bd, v0
	v_rcp_f32_e32 v204, v0
	v_lshlrev_b32_e32 v206, 16, v211
	v_max_f32_e32 v0, 0x358637bd, v205
	v_rcp_f32_e32 v205, v0
	v_and_b32_e32 v207, 0xffff0000, v211
	v_max_f32_e32 v0, 0x358637bd, v206
	v_rcp_f32_e32 v206, v0
	v_lshlrev_b32_e32 v208, 16, v212
	v_max_f32_e32 v0, 0x358637bd, v207
	v_rcp_f32_e32 v207, v0
	v_and_b32_e32 v209, 0xffff0000, v212
	v_max_f32_e32 v0, 0x358637bd, v208
	v_rcp_f32_e32 v208, v0
	v_lshlrev_b32_e32 v210, 16, v213
	v_max_f32_e32 v0, 0x358637bd, v209
	v_rcp_f32_e32 v209, v0
	v_and_b32_e32 v211, 0xffff0000, v213
	v_max_f32_e32 v0, 0x358637bd, v210
	v_rcp_f32_e32 v210, v0
	v_max_f32_e32 v0, 0x358637bd, v211
	v_rcp_f32_e32 v211, v0
	v_pk_mul_f32 v[2:3], v[2:3], v[204:205]
	v_pk_mul_f32 v[172:173], v[172:173], v[206:207]
	v_pk_mul_f32 v[56:57], v[56:57], v[2:3]
	v_pk_mul_f32 v[2:3], v[174:175], v[208:209]
	s_waitcnt vmcnt(11)
	v_lshlrev_b32_e32 v0, 16, v214
	v_pk_mul_f32 v[58:59], v[58:59], v[172:173]
	v_pk_mul_f32 v[172:173], v[202:203], v[210:211]
	v_pk_mul_f32 v[52:53], v[52:53], v[2:3]
	v_and_b32_e32 v3, 0xffff0000, v214
	v_pk_mul_f32 v[54:55], v[54:55], v[172:173]
	v_lshlrev_b32_e32 v172, 16, v215
	v_max_f32_e32 v2, 0x358637bd, v0
	v_and_b32_e32 v173, 0xffff0000, v215
	v_max_f32_e32 v3, 0x358637bd, v3
	v_lshlrev_b32_e32 v174, 16, v216
	v_max_f32_e32 v172, 0x358637bd, v172
	v_and_b32_e32 v175, 0xffff0000, v216
	v_max_f32_e32 v173, 0x358637bd, v173
	v_lshlrev_b32_e32 v202, 16, v217
	v_max_f32_e32 v174, 0x358637bd, v174
	v_and_b32_e32 v203, 0xffff0000, v217
	v_max_f32_e32 v175, 0x358637bd, v175
	v_max_f32_e32 v202, 0x358637bd, v202
	v_max_f32_e32 v203, 0x358637bd, v203
	s_waitcnt vmcnt(9)
	v_lshlrev_b32_e32 v0, 16, v218
	v_and_b32_e32 v205, 0xffff0000, v218
	v_max_f32_e32 v0, 0x358637bd, v0
	v_rcp_f32_e32 v204, v0
	v_lshlrev_b32_e32 v206, 16, v219
	v_max_f32_e32 v0, 0x358637bd, v205
	v_rcp_f32_e32 v205, v0
	v_and_b32_e32 v207, 0xffff0000, v219
	v_max_f32_e32 v0, 0x358637bd, v206
	v_rcp_f32_e32 v206, v0
	v_lshlrev_b32_e32 v208, 16, v220
	v_max_f32_e32 v0, 0x358637bd, v207
	v_rcp_f32_e32 v207, v0
	v_and_b32_e32 v209, 0xffff0000, v220
	v_max_f32_e32 v0, 0x358637bd, v208
	v_rcp_f32_e32 v208, v0
	v_lshlrev_b32_e32 v210, 16, v221
	v_max_f32_e32 v0, 0x358637bd, v209
	v_rcp_f32_e32 v209, v0
	v_and_b32_e32 v211, 0xffff0000, v221
	v_max_f32_e32 v0, 0x358637bd, v210
	v_rcp_f32_e32 v210, v0
	v_max_f32_e32 v0, 0x358637bd, v211
	v_rcp_f32_e32 v211, v0
	v_pk_mul_f32 v[2:3], v[2:3], v[204:205]
	v_lshlrev_b32_e32 v0, 16, v168
	v_pk_mul_f32 v[48:49], v[48:49], v[2:3]
	v_pk_mul_f32 v[2:3], v[174:175], v[208:209]
	v_pk_mul_f32 v[44:45], v[44:45], v[2:3]
	v_and_b32_e32 v3, 0xffff0000, v168
	v_pk_mul_f32 v[172:173], v[172:173], v[206:207]
	v_lshlrev_b32_e32 v168, 16, v169
	v_max_f32_e32 v2, 0x358637bd, v0
	v_pk_mul_f32 v[50:51], v[50:51], v[172:173]
	v_pk_mul_f32 v[172:173], v[202:203], v[210:211]
	v_and_b32_e32 v169, 0xffff0000, v169
	v_max_f32_e32 v3, 0x358637bd, v3
	v_pk_mul_f32 v[46:47], v[46:47], v[172:173]
	v_lshlrev_b32_e32 v172, 16, v170
	v_max_f32_e32 v168, 0x358637bd, v168
	v_and_b32_e32 v173, 0xffff0000, v170
	v_max_f32_e32 v169, 0x358637bd, v169
	v_lshlrev_b32_e32 v174, 16, v171
	v_max_f32_e32 v170, 0x358637bd, v172
	v_and_b32_e32 v175, 0xffff0000, v171
	v_max_f32_e32 v171, 0x358637bd, v173
	v_max_f32_e32 v172, 0x358637bd, v174
	v_max_f32_e32 v173, 0x358637bd, v175
	s_waitcnt vmcnt(8)
	v_lshlrev_b32_e32 v0, 16, v164
	v_and_b32_e32 v174, 0xffff0000, v164
	v_max_f32_e32 v0, 0x358637bd, v0
	v_rcp_f32_e32 v164, v0
	v_lshlrev_b32_e32 v175, 16, v165
	v_max_f32_e32 v0, 0x358637bd, v174
	v_and_b32_e32 v202, 0xffff0000, v165
	v_rcp_f32_e32 v165, v0
	v_max_f32_e32 v0, 0x358637bd, v175
	v_lshlrev_b32_e32 v203, 16, v166
	v_and_b32_e32 v204, 0xffff0000, v166
	v_rcp_f32_e32 v166, v0
	v_max_f32_e32 v0, 0x358637bd, v202
	v_lshlrev_b32_e32 v205, 16, v167
	v_and_b32_e32 v206, 0xffff0000, v167
	v_rcp_f32_e32 v167, v0
	v_max_f32_e32 v0, 0x358637bd, v203
	v_rcp_f32_e32 v174, v0
	v_max_f32_e32 v0, 0x358637bd, v204
	v_rcp_f32_e32 v175, v0
	v_max_f32_e32 v0, 0x358637bd, v205
	v_rcp_f32_e32 v202, v0
	v_max_f32_e32 v0, 0x358637bd, v206
	v_rcp_f32_e32 v203, v0
	v_pk_mul_f32 v[2:3], v[2:3], v[164:165]
	s_waitcnt vmcnt(7)
	v_lshlrev_b32_e32 v0, 16, v160
	v_pk_mul_f32 v[40:41], v[40:41], v[2:3]
	v_pk_mul_f32 v[2:3], v[170:171], v[174:175]
	v_pk_mul_f32 v[36:37], v[36:37], v[2:3]
	v_and_b32_e32 v3, 0xffff0000, v160
	v_pk_mul_f32 v[164:165], v[168:169], v[166:167]
	v_lshlrev_b32_e32 v160, 16, v161
	v_max_f32_e32 v2, 0x358637bd, v0
	v_pk_mul_f32 v[42:43], v[42:43], v[164:165]
	v_pk_mul_f32 v[164:165], v[172:173], v[202:203]
	v_and_b32_e32 v161, 0xffff0000, v161
	v_max_f32_e32 v3, 0x358637bd, v3
	v_pk_mul_f32 v[38:39], v[38:39], v[164:165]
	v_lshlrev_b32_e32 v164, 16, v162
	v_max_f32_e32 v160, 0x358637bd, v160
	v_and_b32_e32 v165, 0xffff0000, v162
	v_max_f32_e32 v161, 0x358637bd, v161
	v_lshlrev_b32_e32 v166, 16, v163
	v_max_f32_e32 v162, 0x358637bd, v164
	v_and_b32_e32 v167, 0xffff0000, v163
	v_max_f32_e32 v163, 0x358637bd, v165
	v_max_f32_e32 v164, 0x358637bd, v166
	v_max_f32_e32 v165, 0x358637bd, v167
	s_waitcnt vmcnt(5)
	v_lshlrev_b32_e32 v0, 16, v156
	v_and_b32_e32 v166, 0xffff0000, v156
	v_max_f32_e32 v0, 0x358637bd, v0
	v_rcp_f32_e32 v156, v0
	v_lshlrev_b32_e32 v167, 16, v157
	v_max_f32_e32 v0, 0x358637bd, v166
	v_and_b32_e32 v168, 0xffff0000, v157
	v_rcp_f32_e32 v157, v0
	v_max_f32_e32 v0, 0x358637bd, v167
	v_lshlrev_b32_e32 v169, 16, v158
	v_and_b32_e32 v170, 0xffff0000, v158
	v_rcp_f32_e32 v158, v0
	v_max_f32_e32 v0, 0x358637bd, v168
	v_lshlrev_b32_e32 v171, 16, v159
	v_and_b32_e32 v172, 0xffff0000, v159
	v_rcp_f32_e32 v159, v0
	v_max_f32_e32 v0, 0x358637bd, v169
	v_rcp_f32_e32 v166, v0
	v_max_f32_e32 v0, 0x358637bd, v170
	v_rcp_f32_e32 v167, v0
	v_max_f32_e32 v0, 0x358637bd, v171
	v_rcp_f32_e32 v168, v0
	v_max_f32_e32 v0, 0x358637bd, v172
	v_rcp_f32_e32 v169, v0
	v_pk_mul_f32 v[2:3], v[2:3], v[156:157]
	v_lshlrev_b32_e32 v0, 16, v152
	v_pk_mul_f32 v[32:33], v[32:33], v[2:3]
	v_pk_mul_f32 v[2:3], v[162:163], v[166:167]
	v_pk_mul_f32 v[28:29], v[28:29], v[2:3]
	v_and_b32_e32 v3, 0xffff0000, v152
	v_pk_mul_f32 v[156:157], v[160:161], v[158:159]
	v_lshlrev_b32_e32 v152, 16, v153
	v_max_f32_e32 v2, 0x358637bd, v0
	v_pk_mul_f32 v[34:35], v[34:35], v[156:157]
	v_pk_mul_f32 v[156:157], v[164:165], v[168:169]
	v_and_b32_e32 v153, 0xffff0000, v153
	v_max_f32_e32 v3, 0x358637bd, v3
	v_pk_mul_f32 v[30:31], v[30:31], v[156:157]
	v_lshlrev_b32_e32 v156, 16, v154
	v_max_f32_e32 v152, 0x358637bd, v152
	v_and_b32_e32 v157, 0xffff0000, v154
	v_max_f32_e32 v153, 0x358637bd, v153
	v_lshlrev_b32_e32 v158, 16, v155
	v_max_f32_e32 v154, 0x358637bd, v156
	v_and_b32_e32 v159, 0xffff0000, v155
	v_max_f32_e32 v155, 0x358637bd, v157
	v_max_f32_e32 v156, 0x358637bd, v158
	v_max_f32_e32 v157, 0x358637bd, v159
	s_waitcnt vmcnt(4)
	v_lshlrev_b32_e32 v0, 16, v148
	v_and_b32_e32 v158, 0xffff0000, v148
	v_max_f32_e32 v0, 0x358637bd, v0
	v_rcp_f32_e32 v148, v0
	v_lshlrev_b32_e32 v159, 16, v149
	v_max_f32_e32 v0, 0x358637bd, v158
	v_and_b32_e32 v160, 0xffff0000, v149
	v_rcp_f32_e32 v149, v0
	v_max_f32_e32 v0, 0x358637bd, v159
	v_lshlrev_b32_e32 v161, 16, v150
	v_and_b32_e32 v162, 0xffff0000, v150
	v_rcp_f32_e32 v150, v0
	v_max_f32_e32 v0, 0x358637bd, v160
	v_lshlrev_b32_e32 v163, 16, v151
	v_and_b32_e32 v164, 0xffff0000, v151
	v_rcp_f32_e32 v151, v0
	v_max_f32_e32 v0, 0x358637bd, v161
	v_rcp_f32_e32 v158, v0
	v_max_f32_e32 v0, 0x358637bd, v162
	v_rcp_f32_e32 v159, v0
	v_max_f32_e32 v0, 0x358637bd, v163
	v_rcp_f32_e32 v160, v0
	v_max_f32_e32 v0, 0x358637bd, v164
	v_rcp_f32_e32 v161, v0
	v_pk_mul_f32 v[2:3], v[2:3], v[148:149]
	s_waitcnt vmcnt(3)
	v_lshlrev_b32_e32 v0, 16, v144
	v_pk_mul_f32 v[24:25], v[24:25], v[2:3]
	v_pk_mul_f32 v[2:3], v[154:155], v[158:159]
	v_pk_mul_f32 v[20:21], v[20:21], v[2:3]
	v_and_b32_e32 v3, 0xffff0000, v144
	v_pk_mul_f32 v[148:149], v[152:153], v[150:151]
	v_lshlrev_b32_e32 v144, 16, v145
	v_max_f32_e32 v2, 0x358637bd, v0
	v_pk_mul_f32 v[26:27], v[26:27], v[148:149]
	v_pk_mul_f32 v[148:149], v[156:157], v[160:161]
	v_and_b32_e32 v145, 0xffff0000, v145
	v_max_f32_e32 v3, 0x358637bd, v3
	v_pk_mul_f32 v[22:23], v[22:23], v[148:149]
	v_lshlrev_b32_e32 v148, 16, v146
	v_max_f32_e32 v144, 0x358637bd, v144
	v_and_b32_e32 v149, 0xffff0000, v146
	v_max_f32_e32 v145, 0x358637bd, v145
	v_lshlrev_b32_e32 v150, 16, v147
	v_max_f32_e32 v146, 0x358637bd, v148
	v_and_b32_e32 v151, 0xffff0000, v147
	v_max_f32_e32 v147, 0x358637bd, v149
	v_max_f32_e32 v148, 0x358637bd, v150
	v_max_f32_e32 v149, 0x358637bd, v151
	s_waitcnt vmcnt(1)
	v_lshlrev_b32_e32 v0, 16, v140
	v_and_b32_e32 v150, 0xffff0000, v140
	v_max_f32_e32 v0, 0x358637bd, v0
	v_rcp_f32_e32 v140, v0
	v_lshlrev_b32_e32 v151, 16, v141
	v_max_f32_e32 v0, 0x358637bd, v150
	v_and_b32_e32 v152, 0xffff0000, v141
	v_rcp_f32_e32 v141, v0
	v_max_f32_e32 v0, 0x358637bd, v151
	v_lshlrev_b32_e32 v153, 16, v142
	v_and_b32_e32 v154, 0xffff0000, v142
	v_rcp_f32_e32 v142, v0
	v_max_f32_e32 v0, 0x358637bd, v152
	v_lshlrev_b32_e32 v155, 16, v143
	v_and_b32_e32 v156, 0xffff0000, v143
	v_rcp_f32_e32 v143, v0
	v_max_f32_e32 v0, 0x358637bd, v153
	v_rcp_f32_e32 v150, v0
	v_max_f32_e32 v0, 0x358637bd, v154
	v_rcp_f32_e32 v151, v0
	v_max_f32_e32 v0, 0x358637bd, v155
	v_rcp_f32_e32 v152, v0
	v_max_f32_e32 v0, 0x358637bd, v156
	v_rcp_f32_e32 v153, v0
	v_pk_mul_f32 v[2:3], v[2:3], v[140:141]
	v_lshlrev_b32_e32 v0, 16, v136
	v_pk_mul_f32 v[16:17], v[16:17], v[2:3]
	v_pk_mul_f32 v[2:3], v[146:147], v[150:151]
	v_pk_mul_f32 v[12:13], v[12:13], v[2:3]
	v_and_b32_e32 v3, 0xffff0000, v136
	v_pk_mul_f32 v[140:141], v[144:145], v[142:143]
	v_lshlrev_b32_e32 v136, 16, v137
	v_max_f32_e32 v2, 0x358637bd, v0
	v_pk_mul_f32 v[18:19], v[18:19], v[140:141]
	v_pk_mul_f32 v[140:141], v[148:149], v[152:153]
	v_and_b32_e32 v137, 0xffff0000, v137
	v_max_f32_e32 v3, 0x358637bd, v3
	v_pk_mul_f32 v[14:15], v[14:15], v[140:141]
	v_lshlrev_b32_e32 v140, 16, v138
	v_max_f32_e32 v136, 0x358637bd, v136
	v_and_b32_e32 v141, 0xffff0000, v138
	v_max_f32_e32 v137, 0x358637bd, v137
	v_lshlrev_b32_e32 v142, 16, v139
	v_max_f32_e32 v138, 0x358637bd, v140
	v_and_b32_e32 v143, 0xffff0000, v139
	v_max_f32_e32 v139, 0x358637bd, v141
	v_max_f32_e32 v140, 0x358637bd, v142
	v_max_f32_e32 v141, 0x358637bd, v143
	s_waitcnt vmcnt(0)
	v_lshlrev_b32_e32 v0, 16, v132
	v_and_b32_e32 v142, 0xffff0000, v132
	v_max_f32_e32 v0, 0x358637bd, v0
	v_rcp_f32_e32 v132, v0
	v_lshlrev_b32_e32 v143, 16, v133
	v_max_f32_e32 v0, 0x358637bd, v142
	v_and_b32_e32 v144, 0xffff0000, v133
	v_rcp_f32_e32 v133, v0
	v_max_f32_e32 v0, 0x358637bd, v143
	v_lshlrev_b32_e32 v145, 16, v134
	v_and_b32_e32 v146, 0xffff0000, v134
	v_rcp_f32_e32 v134, v0
	v_max_f32_e32 v0, 0x358637bd, v144
	v_lshlrev_b32_e32 v147, 16, v135
	v_and_b32_e32 v148, 0xffff0000, v135
	v_rcp_f32_e32 v135, v0
	v_max_f32_e32 v0, 0x358637bd, v145
	v_rcp_f32_e32 v142, v0
	v_max_f32_e32 v0, 0x358637bd, v146
	v_rcp_f32_e32 v143, v0
	v_max_f32_e32 v0, 0x358637bd, v147
	v_rcp_f32_e32 v144, v0
	v_max_f32_e32 v0, 0x358637bd, v148
	v_rcp_f32_e32 v145, v0
	v_pk_mul_f32 v[2:3], v[2:3], v[132:133]
	v_pk_mul_f32 v[132:133], v[136:137], v[134:135]
	v_pk_mul_f32 v[8:9], v[8:9], v[2:3]
	v_pk_mul_f32 v[10:11], v[10:11], v[132:133]
	v_pk_mul_f32 v[2:3], v[138:139], v[142:143]
	v_pk_mul_f32 v[132:133], v[140:141], v[144:145]
	v_pk_mul_f32 v[4:5], v[4:5], v[2:3]
	v_pk_mul_f32 v[6:7], v[6:7], v[132:133]
	s_branch .LBB0_722

.LBB0_727:
	s_and_b32 s21, s76, 1
	s_lshl_b32 s18, s21, 12
	s_bitset1_b32 s18, 11
	s_and_b64 s[42:43], s[48:49], exec
	v_mov_b32_e32 v166, v199
	v_mov_b32_e32 v167, v198
	s_cselect_b32 s18, 0x1800, s18
	s_lshl_b32 s18, s18, 1
	v_add_u32_e32 v0, s89, v166
	v_lshl_add_u32 v2, v167, 3, s78
	v_add_u32_e32 v156, s5, v0
	s_add_u32 s42, s28, s18
	v_ashrrev_i32_e32 v3, 31, v2
	s_addc_u32 s43, s29, 0
	v_ashrrev_i32_e32 v157, 31, v156
	v_lshl_add_u64 v[164:165], v[2:3], 1, s[42:43]
	v_lshlrev_b64 v[132:133], 14, v[156:157]
	v_lshl_add_u64 v[132:133], v[164:165], 0, v[132:133]
	global_load_dwordx4 v[168:171], v[132:133], off
	global_load_dwordx4 v[172:175], v[132:133], off offset:256
	v_add_u32_e32 v162, 16, v156
	v_ashrrev_i32_e32 v163, 31, v162
	v_lshlrev_b64 v[132:133], 14, v[162:163]
	v_lshl_add_u64 v[132:133], v[164:165], 0, v[132:133]
	global_load_dwordx4 v[152:155], v[132:133], off
	global_load_dwordx4 v[148:151], v[132:133], off offset:256
	v_add_u32_e32 v160, 32, v156
	v_ashrrev_i32_e32 v161, 31, v160
	v_lshlrev_b64 v[132:133], 14, v[160:161]
	v_lshl_add_u64 v[132:133], v[164:165], 0, v[132:133]
	global_load_dwordx4 v[144:147], v[132:133], off
	global_load_dwordx4 v[136:139], v[132:133], off offset:256
	v_add_u32_e32 v158, 48, v156
	v_ashrrev_i32_e32 v159, 31, v158
	v_lshlrev_b64 v[132:133], 14, v[158:159]
	v_lshl_add_u64 v[132:133], v[164:165], 0, v[132:133]
	global_load_dwordx4 v[140:143], v[132:133], off
	s_nop 0
	global_load_dwordx4 v[132:135], v[132:133], off offset:256
	s_andn2_b64 vcc, exec, s[40:41]
	s_waitcnt vmcnt(0)
	v_lshlrev_b32_e32 v194, 16, v168
	v_and_b32_e32 v195, 0xffff0000, v168
	v_lshlrev_b32_e32 v196, 16, v169
	v_and_b32_e32 v197, 0xffff0000, v169
	v_lshlrev_b32_e32 v202, 16, v170
	v_and_b32_e32 v203, 0xffff0000, v170
	v_lshlrev_b32_e32 v204, 16, v171
	v_and_b32_e32 v205, 0xffff0000, v171
	v_max_f32_e32 v168, 0x358637bd, v194
	v_max_f32_e32 v169, 0x358637bd, v195
	v_max_f32_e32 v170, 0x358637bd, v196
	v_max_f32_e32 v171, 0x358637bd, v197
	v_pk_mul_f32 v[128:129], v[128:129], v[168:169]
	v_pk_mul_f32 v[130:131], v[130:131], v[170:171]
	v_lshlrev_b32_e32 v168, 16, v172
	v_and_b32_e32 v169, 0xffff0000, v172
	v_lshlrev_b32_e32 v170, 16, v173
	v_and_b32_e32 v171, 0xffff0000, v173
	v_lshlrev_b32_e32 v172, 16, v174
	v_and_b32_e32 v173, 0xffff0000, v174
	v_lshlrev_b32_e32 v174, 16, v175
	v_and_b32_e32 v175, 0xffff0000, v175
	v_max_f32_e32 v168, 0x358637bd, v168
	v_max_f32_e32 v169, 0x358637bd, v169
	v_max_f32_e32 v170, 0x358637bd, v170
	v_max_f32_e32 v171, 0x358637bd, v171
	v_max_f32_e32 v172, 0x358637bd, v172
	v_max_f32_e32 v173, 0x358637bd, v173
	v_max_f32_e32 v174, 0x358637bd, v174
	v_max_f32_e32 v175, 0x358637bd, v175
	v_pk_mul_f32 v[120:121], v[120:121], v[168:169]
	v_pk_mul_f32 v[122:123], v[122:123], v[170:171]
	v_lshlrev_b32_e32 v168, 16, v152
	v_and_b32_e32 v169, 0xffff0000, v152
	v_lshlrev_b32_e32 v170, 16, v153
	v_and_b32_e32 v171, 0xffff0000, v153
	v_pk_mul_f32 v[116:117], v[116:117], v[172:173]
	v_pk_mul_f32 v[118:119], v[118:119], v[174:175]
	v_lshlrev_b32_e32 v172, 16, v154
	v_and_b32_e32 v173, 0xffff0000, v154
	v_lshlrev_b32_e32 v174, 16, v155
	v_and_b32_e32 v175, 0xffff0000, v155
	v_max_f32_e32 v152, 0x358637bd, v168
	v_max_f32_e32 v153, 0x358637bd, v169
	v_max_f32_e32 v154, 0x358637bd, v170
	v_max_f32_e32 v155, 0x358637bd, v171
	v_max_f32_e32 v168, 0x358637bd, v172
	v_max_f32_e32 v169, 0x358637bd, v173
	v_max_f32_e32 v170, 0x358637bd, v174
	v_max_f32_e32 v171, 0x358637bd, v175
	v_pk_mul_f32 v[112:113], v[112:113], v[152:153]
	v_pk_mul_f32 v[114:115], v[114:115], v[154:155]
	v_lshlrev_b32_e32 v152, 16, v148
	v_and_b32_e32 v153, 0xffff0000, v148
	v_lshlrev_b32_e32 v154, 16, v149
	v_and_b32_e32 v155, 0xffff0000, v149
	v_pk_mul_f32 v[108:109], v[108:109], v[168:169]
	v_pk_mul_f32 v[110:111], v[110:111], v[170:171]
	v_lshlrev_b32_e32 v168, 16, v150
	v_and_b32_e32 v169, 0xffff0000, v150
	v_lshlrev_b32_e32 v170, 16, v151
	v_and_b32_e32 v171, 0xffff0000, v151
	v_max_f32_e32 v148, 0x358637bd, v152
	v_max_f32_e32 v149, 0x358637bd, v153
	v_max_f32_e32 v150, 0x358637bd, v154
	v_max_f32_e32 v151, 0x358637bd, v155
	v_max_f32_e32 v152, 0x358637bd, v168
	v_max_f32_e32 v153, 0x358637bd, v169
	v_max_f32_e32 v154, 0x358637bd, v170
	v_max_f32_e32 v155, 0x358637bd, v171
	v_pk_mul_f32 v[104:105], v[104:105], v[148:149]
	v_pk_mul_f32 v[106:107], v[106:107], v[150:151]
	v_lshlrev_b32_e32 v148, 16, v144
	v_and_b32_e32 v149, 0xffff0000, v144
	v_lshlrev_b32_e32 v150, 16, v145
	v_and_b32_e32 v151, 0xffff0000, v145
	v_pk_mul_f32 v[100:101], v[100:101], v[152:153]
	v_pk_mul_f32 v[102:103], v[102:103], v[154:155]
	v_lshlrev_b32_e32 v152, 16, v146
	v_and_b32_e32 v153, 0xffff0000, v146
	v_lshlrev_b32_e32 v154, 16, v147
	v_and_b32_e32 v155, 0xffff0000, v147
	v_max_f32_e32 v144, 0x358637bd, v148
	v_max_f32_e32 v145, 0x358637bd, v149
	v_max_f32_e32 v146, 0x358637bd, v150
	v_max_f32_e32 v147, 0x358637bd, v151
	v_max_f32_e32 v148, 0x358637bd, v152
	v_max_f32_e32 v149, 0x358637bd, v153
	v_max_f32_e32 v150, 0x358637bd, v154
	v_max_f32_e32 v151, 0x358637bd, v155
	v_pk_mul_f32 v[96:97], v[96:97], v[144:145]
	v_pk_mul_f32 v[98:99], v[98:99], v[146:147]
	v_lshlrev_b32_e32 v144, 16, v136
	v_and_b32_e32 v145, 0xffff0000, v136
	v_lshlrev_b32_e32 v146, 16, v137
	v_and_b32_e32 v147, 0xffff0000, v137
	v_pk_mul_f32 v[92:93], v[92:93], v[148:149]
	v_pk_mul_f32 v[94:95], v[94:95], v[150:151]
	v_lshlrev_b32_e32 v148, 16, v138
	v_and_b32_e32 v149, 0xffff0000, v138
	v_lshlrev_b32_e32 v150, 16, v139
	v_and_b32_e32 v151, 0xffff0000, v139
	v_max_f32_e32 v136, 0x358637bd, v144
	v_max_f32_e32 v137, 0x358637bd, v145
	v_max_f32_e32 v138, 0x358637bd, v146
	v_max_f32_e32 v139, 0x358637bd, v147
	v_pk_mul_f32 v[88:89], v[88:89], v[136:137]
	v_pk_mul_f32 v[90:91], v[90:91], v[138:139]
	v_lshlrev_b32_e32 v136, 16, v140
	v_and_b32_e32 v137, 0xffff0000, v140
	v_lshlrev_b32_e32 v138, 16, v141
	v_and_b32_e32 v139, 0xffff0000, v141
	v_lshlrev_b32_e32 v140, 16, v142
	v_and_b32_e32 v141, 0xffff0000, v142
	v_max_f32_e32 v136, 0x358637bd, v136
	v_max_f32_e32 v137, 0x358637bd, v137
	v_max_f32_e32 v140, 0x358637bd, v140
	v_max_f32_e32 v141, 0x358637bd, v141
	v_lshlrev_b32_e32 v142, 16, v143
	v_and_b32_e32 v143, 0xffff0000, v143
	v_max_f32_e32 v138, 0x358637bd, v138
	v_max_f32_e32 v139, 0x358637bd, v139
	v_pk_mul_f32 v[80:81], v[80:81], v[136:137]
	v_pk_mul_f32 v[76:77], v[76:77], v[140:141]
	v_lshlrev_b32_e32 v136, 16, v132
	v_and_b32_e32 v137, 0xffff0000, v132
	v_lshlrev_b32_e32 v140, 16, v134
	v_and_b32_e32 v141, 0xffff0000, v134
	v_pk_mul_f32 v[82:83], v[82:83], v[138:139]
	v_lshlrev_b32_e32 v138, 16, v133
	v_and_b32_e32 v139, 0xffff0000, v133
	v_max_f32_e32 v132, v136, v136
	v_max_f32_e32 v133, v137, v137
	v_max_f32_e32 v136, v140, v140
	v_add_u32_e32 v140, s95, v0
	v_max_f32_e32 v142, 0x358637bd, v142
	v_max_f32_e32 v143, 0x358637bd, v143
	v_max_f32_e32 v136, 0x358637bd, v136
	v_max_f32_e32 v137, 0x358637bd, v141
	v_ashrrev_i32_e32 v141, 31, v140
	v_pk_mul_f32 v[78:79], v[78:79], v[142:143]
	v_lshlrev_b32_e32 v142, 16, v135
	v_and_b32_e32 v143, 0xffff0000, v135
	v_pk_mul_f32 v[136:137], v[68:69], v[136:137]
	v_lshlrev_b64 v[68:69], 14, v[140:141]
	v_max_f32_e32 v144, 0x358637bd, v148
	v_max_f32_e32 v145, 0x358637bd, v149
	v_max_f32_e32 v132, 0x358637bd, v132
	v_max_f32_e32 v133, 0x358637bd, v133
	v_max_f32_e32 v134, 0x358637bd, v138
	v_max_f32_e32 v135, 0x358637bd, v139
	v_lshl_add_u64 v[68:69], v[164:165], 0, v[68:69]
	v_pk_mul_f32 v[84:85], v[84:85], v[144:145]
	v_max_f32_e32 v138, v142, v142
	v_max_f32_e32 v139, v143, v143
	v_pk_mul_f32 v[132:133], v[72:73], v[132:133]
	v_pk_mul_f32 v[134:135], v[74:75], v[134:135]
	global_load_dwordx4 v[72:75], v[68:69], off
	global_load_dwordx4 v[142:145], v[68:69], off offset:256
	v_add_u32_e32 v68, 16, v140
	v_ashrrev_i32_e32 v69, 31, v68
	v_lshlrev_b64 v[68:69], 14, v[68:69]
	v_max_f32_e32 v146, 0x358637bd, v150
	v_max_f32_e32 v147, 0x358637bd, v151
	v_lshl_add_u64 v[68:69], v[164:165], 0, v[68:69]
	v_pk_mul_f32 v[86:87], v[86:87], v[146:147]
	global_load_dwordx4 v[146:149], v[68:69], off
	global_load_dwordx4 v[150:153], v[68:69], off offset:256
	v_add_u32_e32 v68, 32, v140
	v_ashrrev_i32_e32 v69, 31, v68
	v_lshlrev_b64 v[68:69], 14, v[68:69]
	v_lshl_add_u64 v[68:69], v[164:165], 0, v[68:69]
	global_load_dwordx4 v[168:171], v[68:69], off
	global_load_dwordx4 v[172:175], v[68:69], off offset:256
	v_add_u32_e32 v68, 48, v140
	v_ashrrev_i32_e32 v69, 31, v68
	v_lshlrev_b64 v[68:69], 14, v[68:69]
	v_max_f32_e32 v194, 0x358637bd, v202
	v_max_f32_e32 v195, 0x358637bd, v203
	v_max_f32_e32 v196, 0x358637bd, v204
	v_max_f32_e32 v197, 0x358637bd, v205
	v_max_f32_e32 v138, 0x358637bd, v138
	v_max_f32_e32 v139, 0x358637bd, v139
	v_lshl_add_u64 v[68:69], v[164:165], 0, v[68:69]
	v_pk_mul_f32 v[124:125], v[124:125], v[194:195]
	v_pk_mul_f32 v[126:127], v[126:127], v[196:197]
	v_pk_mul_f32 v[138:139], v[70:71], v[138:139]
	global_load_dwordx4 v[194:197], v[68:69], off
	s_nop 0
	global_load_dwordx4 v[68:71], v[68:69], off offset:256
	s_waitcnt vmcnt(7)
	v_lshlrev_b32_e32 v154, 16, v72
	v_and_b32_e32 v155, 0xffff0000, v72
	v_lshlrev_b32_e32 v164, 16, v73
	v_and_b32_e32 v165, 0xffff0000, v73
	v_lshlrev_b32_e32 v202, 16, v74
	v_and_b32_e32 v203, 0xffff0000, v74
	v_lshlrev_b32_e32 v204, 16, v75
	v_and_b32_e32 v205, 0xffff0000, v75
	v_max_f32_e32 v72, 0x358637bd, v154
	v_max_f32_e32 v73, 0x358637bd, v155
	v_max_f32_e32 v74, 0x358637bd, v164
	v_max_f32_e32 v75, 0x358637bd, v165
	v_pk_mul_f32 v[64:65], v[64:65], v[72:73]
	v_pk_mul_f32 v[66:67], v[66:67], v[74:75]
	s_waitcnt vmcnt(6)
	v_lshlrev_b32_e32 v72, 16, v142
	v_and_b32_e32 v73, 0xffff0000, v142
	v_lshlrev_b32_e32 v74, 16, v143
	v_and_b32_e32 v75, 0xffff0000, v143
	v_lshlrev_b32_e32 v142, 16, v144
	v_and_b32_e32 v143, 0xffff0000, v144
	v_lshlrev_b32_e32 v144, 16, v145
	v_and_b32_e32 v145, 0xffff0000, v145
	v_max_f32_e32 v72, 0x358637bd, v72
	v_max_f32_e32 v73, 0x358637bd, v73
	v_max_f32_e32 v74, 0x358637bd, v74
	v_max_f32_e32 v75, 0x358637bd, v75
	v_max_f32_e32 v142, 0x358637bd, v142
	v_max_f32_e32 v143, 0x358637bd, v143
	v_max_f32_e32 v144, 0x358637bd, v144
	v_max_f32_e32 v145, 0x358637bd, v145
	v_pk_mul_f32 v[56:57], v[56:57], v[72:73]
	v_pk_mul_f32 v[58:59], v[58:59], v[74:75]
	v_pk_mul_f32 v[52:53], v[52:53], v[142:143]
	v_pk_mul_f32 v[54:55], v[54:55], v[144:145]
	s_waitcnt vmcnt(5)
	v_lshlrev_b32_e32 v72, 16, v146
	v_and_b32_e32 v73, 0xffff0000, v146
	v_lshlrev_b32_e32 v74, 16, v147
	v_and_b32_e32 v75, 0xffff0000, v147
	v_lshlrev_b32_e32 v142, 16, v148
	v_and_b32_e32 v143, 0xffff0000, v148
	v_lshlrev_b32_e32 v144, 16, v149
	v_and_b32_e32 v145, 0xffff0000, v149
	v_max_f32_e32 v72, 0x358637bd, v72
	v_max_f32_e32 v73, 0x358637bd, v73
	v_max_f32_e32 v74, 0x358637bd, v74
	v_max_f32_e32 v75, 0x358637bd, v75
	v_max_f32_e32 v142, 0x358637bd, v142
	v_max_f32_e32 v143, 0x358637bd, v143
	v_max_f32_e32 v144, 0x358637bd, v144
	v_max_f32_e32 v145, 0x358637bd, v145
	v_pk_mul_f32 v[48:49], v[48:49], v[72:73]
	v_pk_mul_f32 v[50:51], v[50:51], v[74:75]
	v_pk_mul_f32 v[44:45], v[44:45], v[142:143]
	v_pk_mul_f32 v[46:47], v[46:47], v[144:145]
	s_waitcnt vmcnt(4)
	v_lshlrev_b32_e32 v72, 16, v150
	v_and_b32_e32 v73, 0xffff0000, v150
	v_lshlrev_b32_e32 v74, 16, v151
	v_and_b32_e32 v75, 0xffff0000, v151
	v_lshlrev_b32_e32 v142, 16, v152
	v_and_b32_e32 v143, 0xffff0000, v152
	v_lshlrev_b32_e32 v144, 16, v153
	v_and_b32_e32 v145, 0xffff0000, v153
	v_max_f32_e32 v72, 0x358637bd, v72
	v_max_f32_e32 v73, 0x358637bd, v73
	v_max_f32_e32 v74, 0x358637bd, v74
	v_max_f32_e32 v75, 0x358637bd, v75
	v_max_f32_e32 v142, 0x358637bd, v142
	v_max_f32_e32 v143, 0x358637bd, v143
	v_max_f32_e32 v144, 0x358637bd, v144
	v_max_f32_e32 v145, 0x358637bd, v145
	v_pk_mul_f32 v[40:41], v[40:41], v[72:73]
	v_pk_mul_f32 v[42:43], v[42:43], v[74:75]
	v_pk_mul_f32 v[36:37], v[36:37], v[142:143]
	v_pk_mul_f32 v[38:39], v[38:39], v[144:145]
	s_waitcnt vmcnt(3)
	v_lshlrev_b32_e32 v72, 16, v168
	v_and_b32_e32 v73, 0xffff0000, v168
	v_lshlrev_b32_e32 v74, 16, v169
	v_and_b32_e32 v75, 0xffff0000, v169
	v_lshlrev_b32_e32 v142, 16, v170
	v_and_b32_e32 v143, 0xffff0000, v170
	v_lshlrev_b32_e32 v144, 16, v171
	v_and_b32_e32 v145, 0xffff0000, v171
	v_max_f32_e32 v72, 0x358637bd, v72
	v_max_f32_e32 v73, 0x358637bd, v73
	v_max_f32_e32 v74, 0x358637bd, v74
	v_max_f32_e32 v75, 0x358637bd, v75
	v_max_f32_e32 v142, 0x358637bd, v142
	v_max_f32_e32 v143, 0x358637bd, v143
	v_max_f32_e32 v144, 0x358637bd, v144
	v_max_f32_e32 v145, 0x358637bd, v145
	v_pk_mul_f32 v[32:33], v[32:33], v[72:73]
	v_pk_mul_f32 v[34:35], v[34:35], v[74:75]
	v_pk_mul_f32 v[28:29], v[28:29], v[142:143]
	v_pk_mul_f32 v[30:31], v[30:31], v[144:145]
	s_waitcnt vmcnt(2)
	v_lshlrev_b32_e32 v72, 16, v172
	v_and_b32_e32 v73, 0xffff0000, v172
	v_lshlrev_b32_e32 v74, 16, v173
	v_and_b32_e32 v75, 0xffff0000, v173
	v_lshlrev_b32_e32 v142, 16, v174
	v_and_b32_e32 v143, 0xffff0000, v174
	v_lshlrev_b32_e32 v144, 16, v175
	v_and_b32_e32 v145, 0xffff0000, v175
	v_max_f32_e32 v72, 0x358637bd, v72
	v_max_f32_e32 v73, 0x358637bd, v73
	v_max_f32_e32 v74, 0x358637bd, v74
	v_max_f32_e32 v75, 0x358637bd, v75
	v_max_f32_e32 v142, 0x358637bd, v142
	v_max_f32_e32 v143, 0x358637bd, v143
	v_max_f32_e32 v144, 0x358637bd, v144
	v_max_f32_e32 v145, 0x358637bd, v145
	v_pk_mul_f32 v[24:25], v[24:25], v[72:73]
	v_pk_mul_f32 v[26:27], v[26:27], v[74:75]
	v_pk_mul_f32 v[20:21], v[20:21], v[142:143]
	v_pk_mul_f32 v[22:23], v[22:23], v[144:145]
	s_waitcnt vmcnt(1)
	v_lshlrev_b32_e32 v72, 16, v194
	v_and_b32_e32 v73, 0xffff0000, v194
	v_lshlrev_b32_e32 v74, 16, v195
	v_and_b32_e32 v75, 0xffff0000, v195
	v_lshlrev_b32_e32 v142, 16, v196
	v_and_b32_e32 v143, 0xffff0000, v196
	v_lshlrev_b32_e32 v144, 16, v197
	v_and_b32_e32 v145, 0xffff0000, v197
	v_max_f32_e32 v72, 0x358637bd, v72
	v_max_f32_e32 v73, 0x358637bd, v73
	v_max_f32_e32 v74, 0x358637bd, v74
	v_max_f32_e32 v75, 0x358637bd, v75
	v_max_f32_e32 v142, 0x358637bd, v142
	v_max_f32_e32 v143, 0x358637bd, v143
	v_max_f32_e32 v144, 0x358637bd, v144
	v_max_f32_e32 v145, 0x358637bd, v145
	v_pk_mul_f32 v[16:17], v[16:17], v[72:73]
	v_pk_mul_f32 v[18:19], v[18:19], v[74:75]
	v_pk_mul_f32 v[12:13], v[12:13], v[142:143]
	v_pk_mul_f32 v[14:15], v[14:15], v[144:145]
	s_waitcnt vmcnt(0)
	v_lshlrev_b32_e32 v72, 16, v68
	v_and_b32_e32 v73, 0xffff0000, v68
	v_lshlrev_b32_e32 v74, 16, v69
	v_and_b32_e32 v75, 0xffff0000, v69
	v_lshlrev_b32_e32 v142, 16, v70
	v_and_b32_e32 v143, 0xffff0000, v70
	v_lshlrev_b32_e32 v144, 16, v71
	v_and_b32_e32 v145, 0xffff0000, v71
	v_max_f32_e32 v68, v72, v72
	v_max_f32_e32 v69, v73, v73
	v_max_f32_e32 v70, v74, v74
	v_max_f32_e32 v71, v75, v75
	v_max_f32_e32 v154, 0x358637bd, v202
	v_max_f32_e32 v155, 0x358637bd, v203
	v_max_f32_e32 v164, 0x358637bd, v204
	v_max_f32_e32 v165, 0x358637bd, v205
	v_max_f32_e32 v68, 0x358637bd, v68
	v_max_f32_e32 v69, 0x358637bd, v69
	v_max_f32_e32 v70, 0x358637bd, v70
	v_max_f32_e32 v71, 0x358637bd, v71
	v_max_f32_e32 v72, 0x358637bd, v142
	v_max_f32_e32 v73, 0x358637bd, v143
	v_max_f32_e32 v74, 0x358637bd, v144
	v_max_f32_e32 v75, 0x358637bd, v145
	v_pk_mul_f32 v[60:61], v[60:61], v[154:155]
	v_pk_mul_f32 v[62:63], v[62:63], v[164:165]
	v_pk_mul_f32 v[68:69], v[8:9], v[68:69]
	v_pk_mul_f32 v[10:11], v[10:11], v[70:71]
	v_pk_mul_f32 v[8:9], v[4:5], v[72:73]
	v_pk_mul_f32 v[4:5], v[6:7], v[74:75]
	s_cbranch_vccnz .LBB0_742
	s_ashr_i32 s40, s76, 2
	s_ashr_i32 s41, s40, 31
	s_lshl_b64 s[42:43], s[40:41], 18
	s_add_u32 s22, s26, s42
	v_lshlrev_b32_e32 v6, 4, v167
	s_addc_u32 s46, s27, s43
	s_xor_b32 s47, s21, 1
	s_lshl_b32 s18, s21, 17
	v_add3_u32 v6, s55, v166, v6
	s_add_u32 s42, s22, s18
	v_ashrrev_i32_e32 v7, 31, v6
	s_addc_u32 s43, s46, 0
	v_lshl_add_u64 v[70:71], v[6:7], 4, s[42:43]
	s_movk_i32 s18, 0x2000
	v_add_co_u32_e32 v72, vcc, s18, v70
	global_store_dwordx4 v[70:71], v[64:67], off sc1
	v_addc_co_u32_e32 v73, vcc, 0, v71, vcc
	global_store_dwordx4 v[72:73], v[60:63], off sc1
	v_add_co_u32_e32 v72, vcc, s3, v70
	s_mov_b32 s18, 0x8000
	s_nop 0
	v_addc_co_u32_e32 v73, vcc, 0, v71, vcc
	global_store_dwordx4 v[72:73], v[56:59], off sc1
	v_add_co_u32_e32 v72, vcc, s72, v70
	s_nop 1
	v_addc_co_u32_e32 v73, vcc, 0, v71, vcc
	global_store_dwordx4 v[72:73], v[52:55], off sc1
	v_add_co_u32_e32 v72, vcc, s18, v70
	s_mov_b32 s18, 0xa000
	s_nop 0
	v_addc_co_u32_e32 v73, vcc, 0, v71, vcc
	global_store_dwordx4 v[72:73], v[48:51], off sc1
	v_add_co_u32_e32 v72, vcc, s18, v70
	s_mov_b32 s18, 0xc000
	s_nop 0
	v_addc_co_u32_e32 v73, vcc, 0, v71, vcc
	global_store_dwordx4 v[72:73], v[44:47], off sc1
	v_add_co_u32_e32 v72, vcc, s18, v70
	s_mov_b32 s18, 0xe000
	s_nop 0
	v_addc_co_u32_e32 v73, vcc, 0, v71, vcc
	global_store_dwordx4 v[72:73], v[40:43], off sc1
	v_add_co_u32_e32 v72, vcc, s18, v70
	s_mov_b32 s18, 0x12000
	s_nop 0
	v_addc_co_u32_e32 v73, vcc, 0, v71, vcc
	global_store_dwordx4 v[72:73], v[36:39], off sc1
	v_add_co_u32_e32 v72, vcc, s68, v70
	s_nop 1
	v_addc_co_u32_e32 v73, vcc, 0, v71, vcc
	global_store_dwordx4 v[72:73], v[32:35], off sc1
	v_add_co_u32_e32 v72, vcc, s18, v70
	s_mov_b32 s18, 0x14000
	s_nop 0
	v_addc_co_u32_e32 v73, vcc, 0, v71, vcc
	global_store_dwordx4 v[72:73], v[28:31], off sc1
	v_add_co_u32_e32 v72, vcc, s18, v70
	s_mov_b32 s18, 0x16000
	s_nop 0
	v_addc_co_u32_e32 v73, vcc, 0, v71, vcc
	global_store_dwordx4 v[72:73], v[24:27], off sc1
	v_add_co_u32_e32 v72, vcc, s18, v70
	s_mov_b32 s18, 0x18000
	s_nop 0
	v_addc_co_u32_e32 v73, vcc, 0, v71, vcc
	global_store_dwordx4 v[72:73], v[20:23], off sc1
	v_add_co_u32_e32 v72, vcc, s18, v70
	s_mov_b32 s18, 0x1a000
	s_nop 0
	v_addc_co_u32_e32 v73, vcc, 0, v71, vcc
	global_store_dwordx4 v[72:73], v[16:19], off sc1
	v_add_co_u32_e32 v72, vcc, s18, v70
	s_mov_b32 s18, 0x1c000
	s_nop 0
	v_addc_co_u32_e32 v73, vcc, 0, v71, vcc
	global_store_dwordx4 v[72:73], v[12:15], off sc1
	v_add_co_u32_e32 v72, vcc, s18, v70
	s_nop 1
	v_addc_co_u32_e32 v73, vcc, 0, v71, vcc
	global_store_dwordx2 v[72:73], v[68:69], off sc1
	global_store_dwordx2 v[72:73], v[10:11], off offset:8 sc1
	v_add_co_u32_e32 v10, vcc, 0x1e000, v70
	s_nop 1
	v_addc_co_u32_e32 v11, vcc, 0, v71, vcc
	global_store_dwordx2 v[10:11], v[8:9], off sc1
	global_store_dwordx2 v[10:11], v[4:5], off offset:8 sc1
	s_waitcnt vmcnt(0)
	v_cmp_eq_u32_e32 vcc, 0, v6
	s_barrier
	s_and_saveexec_b64 s[42:43], vcc
	s_cbranch_execz .LBB0_743
	s_lshl_b32 s40, s40, 4
	s_ashr_i32 s41, s40, 31
	s_lshl_b64 s[40:41], s[40:41], 2
	s_add_u32 s40, s30, s40
	s_addc_u32 s41, s56, s41
	s_lshl_b32 s18, s21, 5
	v_mov_b32_e32 v4, s18
	s_lshl_b32 s18, s47, 5
	s_waitcnt vmcnt(0)
	global_store_dword v4, v181, s[40:41] sc1
	s_add_u32 s40, s40, s18
	s_addc_u32 s41, s41, 0
	s_mov_b32 s21, 0x1000000
	s_branch .LBB0_732
